# v24: v20 + LDS-DMA issued before the ds_reads in 9 of the 8-read (SP2/SP4) K-loop load segments
# baseline (speedup 1.0000x reference)
; #define PG8_WAIT_V(n) asm volatile("s_waitcnt vmcnt(" #n ")" ::: "memory")
; #define PG8_WAIT_L(n) asm volatile("s_waitcnt lgkmcnt(" #n ")" ::: "memory")
; #define PG8_BAR __builtin_amdgcn_s_barrier()
; #define PG8_SCHED __builtin_amdgcn_sched_barrier(0)
;     ...
;             PG8_LDB(B0, 0, 0); PG8_LDB(B1, 0, 1); PG8_SCHED; PG8_LDA(At, 0, 0); PG8_STAGE(PG8_SA(1, 1), a1 + hstepA, voffA);
;             PG8_WAIT_V(8); PG8_WAIT_L(0); PG8_BAR; PG8_MMA(0, 0, At, B0); PG8_MMA(0, 1, At, B1); PG8_BAR; PG8_SCHED;
;             if constexpr (!HALFU) PG8_LDA(At, 0, 1); PG8_STAGE(PG8_SB(0, 0), b2, voffB); PG8_STAGE(PG8_SB(0, 1), b2 + hstep, voffB); PG8_STAGE(PG8_SA(0, 0), a2, voffA);
;             PG8_WAIT_V(8); PG8_WAIT_L(0); PG8_BAR; if constexpr (!HALFU) { PG8_MMA(1, 0, At, B0); PG8_MMA(1, 1, At, B1); } PG8_BAR; PG8_SCHED;
.LBB0_317:
	s_add_u32 s98, s14, 0x80
	s_addc_u32 s99, s15, 0
	s_mov_b32 m0, s49
	s_nop 0
	global_load_lds_dwordx4 v252, s[98:99]
	s_mov_b32 m0, s50
	s_nop 0
	global_load_lds_dwordx4 v146, s[98:99]
	ds_read_b128 v[128:131], v155
	ds_read_b128 v[132:135], v155 offset:1024
	ds_read_b128 v[164:167], v155 offset:2048
	ds_read_b128 v[168:171], v155 offset:3072
	ds_read_b128 v[172:175], v156
	ds_read_b128 v[176:179], v156 offset:1024
	ds_read_b128 v[180:183], v156 offset:2048
	ds_read_b128 v[184:187], v156 offset:3072
	s_add_u32 s30, s14, 0x100
	s_addc_u32 s31, s15, 0
	s_cmp_eq_u32 s58, 28
	s_cselect_b32 s38, s23, s30
	s_cselect_b32 s39, s7, s31
	s_cselect_b32 s36, s55, s56
	s_cselect_b32 s37, s21, s57
	s_add_u32 s34, s38, 0x80
	s_addc_u32 s35, s39, 0
	s_add_u32 s14, s14, 0x80080
	s_addc_u32 s15, s15, 0
	s_add_i32 m0, s29, 0xc000
	ds_read_b128 v[188:191], v157
	ds_read_b128 v[192:195], v157 offset:1024
	ds_read_b128 v[196:199], v157 offset:2048
	ds_read_b128 v[200:203], v157 offset:3072
	ds_read_b128 v[204:207], v157 offset:4096
	ds_read_b128 v[208:211], v157 offset:5120
	ds_read_b128 v[212:215], v157 offset:6144
	ds_read_b128 v[216:219], v157 offset:7168
	global_load_lds_dwordx4 v252, s[14:15]
	s_add_i32 m0, s29, 0xe000
	s_nop 0
	global_load_lds_dwordx4 v146, s[14:15]
	s_waitcnt vmcnt(8)
	s_waitcnt lgkmcnt(0)
	s_barrier
	s_setprio 1
	s_waitcnt lgkmcnt(0)
	v_mfma_scale_f32_16x16x128_f8f6f4 v[124:127], v[128:135], v[188:195], v[124:127], v158, v158 op_sel_hi:[0,0,0]
	v_mfma_scale_f32_16x16x128_f8f6f4 v[120:123], v[164:171], v[188:195], v[120:123], v158, v158 op_sel_hi:[0,0,0]
	v_mfma_scale_f32_16x16x128_f8f6f4 v[108:111], v[128:135], v[196:203], v[108:111], v158, v158 op_sel_hi:[0,0,0]
	v_mfma_scale_f32_16x16x128_f8f6f4 v[104:107], v[164:171], v[196:203], v[104:107], v158, v158 op_sel_hi:[0,0,0]
	v_mfma_scale_f32_16x16x128_f8f6f4 v[136:139], v[128:135], v[204:211], v[92:95], v158, v158 op_sel_hi:[0,0,0]
	v_mfma_scale_f32_16x16x128_f8f6f4 v[220:223], v[164:171], v[204:211], v[88:91], v158, v158 op_sel_hi:[0,0,0]
	v_mfma_scale_f32_16x16x128_f8f6f4 v[224:227], v[128:135], v[212:219], v[76:79], v158, v158 op_sel_hi:[0,0,0]
	v_mfma_scale_f32_16x16x128_f8f6f4 v[228:231], v[164:171], v[212:219], v[72:75], v158, v158 op_sel_hi:[0,0,0]
	s_setprio 0
	s_setprio 1
	v_mfma_scale_f32_16x16x128_f8f6f4 v[116:119], v[172:179], v[188:195], v[116:119], v158, v158 op_sel_hi:[0,0,0]
	v_mfma_scale_f32_16x16x128_f8f6f4 v[112:115], v[180:187], v[188:195], v[112:115], v158, v158 op_sel_hi:[0,0,0]
	v_mfma_scale_f32_16x16x128_f8f6f4 v[100:103], v[172:179], v[196:203], v[100:103], v158, v158 op_sel_hi:[0,0,0]
	v_mfma_scale_f32_16x16x128_f8f6f4 v[96:99], v[180:187], v[196:203], v[96:99], v158, v158 op_sel_hi:[0,0,0]
	v_mfma_scale_f32_16x16x128_f8f6f4 v[188:191], v[172:179], v[204:211], v[84:87], v158, v158 op_sel_hi:[0,0,0]
	v_mfma_scale_f32_16x16x128_f8f6f4 v[192:195], v[180:187], v[204:211], v[80:83], v158, v158 op_sel_hi:[0,0,0]
	v_mfma_scale_f32_16x16x128_f8f6f4 v[196:199], v[172:179], v[212:219], v[68:71], v158, v158 op_sel_hi:[0,0,0]
	v_mfma_scale_f32_16x16x128_f8f6f4 v[200:203], v[180:187], v[212:219], v[64:67], v158, v158 op_sel_hi:[0,0,0]
	s_setprio 0
	s_barrier
	s_add_i32 s14, s53, s40
	s_mov_b32 m0, s14
	s_nop 1
	global_load_lds_dwordx4 v144, s[36:37]
	s_add_i32 m0, s14, 0x2000
	s_add_u32 s14, s36, 0x80000
	s_addc_u32 s15, s37, 0
	s_add_i32 s59, s54, s40
	global_load_lds_dwordx4 v148, s[36:37]
	s_mov_b32 m0, s59
	s_nop 0
	global_load_lds_dwordx4 v144, s[14:15]
	s_add_i32 m0, s59, 0x2000
	s_nop 0
	global_load_lds_dwordx4 v148, s[14:15]
	ds_read_b128 v[64:67], v157 offset:16384
	ds_read_b128 v[68:71], v157 offset:17408
	ds_read_b128 v[72:75], v157 offset:18432
	ds_read_b128 v[76:79], v157 offset:19456
	ds_read_b128 v[80:83], v157 offset:20480
	ds_read_b128 v[84:87], v157 offset:21504
	ds_read_b128 v[88:91], v157 offset:22528
	ds_read_b128 v[92:95], v157 offset:23552
	s_waitcnt vmcnt(4)
	s_waitcnt lgkmcnt(0)
	s_barrier
	s_setprio 1
	s_waitcnt lgkmcnt(0)
	v_mfma_scale_f32_16x16x128_f8f6f4 v[60:63], v[128:135], v[64:71], v[60:63], v158, v158 op_sel_hi:[0,0,0]
	v_mfma_scale_f32_16x16x128_f8f6f4 v[56:59], v[164:171], v[64:71], v[56:59], v158, v158 op_sel_hi:[0,0,0]
	v_mfma_scale_f32_16x16x128_f8f6f4 v[204:207], v[128:135], v[72:79], v[44:47], v158, v158 op_sel_hi:[0,0,0]
	v_mfma_scale_f32_16x16x128_f8f6f4 v[208:211], v[164:171], v[72:79], v[40:43], v158, v158 op_sel_hi:[0,0,0]
	v_mfma_scale_f32_16x16x128_f8f6f4 v[212:215], v[128:135], v[80:87], v[28:31], v158, v158 op_sel_hi:[0,0,0]
	v_mfma_scale_f32_16x16x128_f8f6f4 v[216:219], v[164:171], v[80:87], v[24:27], v158, v158 op_sel_hi:[0,0,0]
	v_mfma_scale_f32_16x16x128_f8f6f4 v[232:235], v[128:135], v[88:95], v[12:15], v158, v158 op_sel_hi:[0,0,0]
	v_mfma_scale_f32_16x16x128_f8f6f4 v[236:239], v[164:171], v[88:95], v[8:11], v158, v158 op_sel_hi:[0,0,0]
	s_setprio 0
	s_setprio 1
	v_mfma_scale_f32_16x16x128_f8f6f4 v[52:55], v[172:179], v[64:71], v[52:55], v158, v158 op_sel_hi:[0,0,0]
	v_mfma_scale_f32_16x16x128_f8f6f4 v[48:51], v[180:187], v[64:71], v[48:51], v158, v158 op_sel_hi:[0,0,0]
	v_mfma_scale_f32_16x16x128_f8f6f4 v[240:243], v[172:179], v[72:79], v[36:39], v158, v158 op_sel_hi:[0,0,0]
	v_mfma_scale_f32_16x16x128_f8f6f4 v[244:247], v[180:187], v[72:79], v[32:35], v158, v158 op_sel_hi:[0,0,0]
	v_mfma_scale_f32_16x16x128_f8f6f4 v[248:251], v[172:179], v[80:87], v[20:23], v158, v158 op_sel_hi:[0,0,0]
	v_mfma_scale_f32_16x16x128_f8f6f4 v[150:153], v[180:187], v[80:87], v[16:19], v158, v158 op_sel_hi:[0,0,0]
	v_mfma_scale_f32_16x16x128_f8f6f4 v[160:163], v[172:179], v[88:95], v[4:7], v158, v158 op_sel_hi:[0,0,0]
	v_mfma_scale_f32_16x16x128_f8f6f4 v[140:143], v[180:187], v[88:95], v[0:3], v158, v158 op_sel_hi:[0,0,0]
	s_setprio 0
	s_barrier
; #define PG8_WAIT_V(n) asm volatile("s_waitcnt vmcnt(" #n ")" ::: "memory")
; #define PG8_WAIT_L(n) asm volatile("s_waitcnt lgkmcnt(" #n ")" ::: "memory")
; #define PG8_BAR __builtin_amdgcn_s_barrier()
; #define PG8_SCHED __builtin_amdgcn_sched_barrier(0)
;     ...
;             PG8_LDB(B0, 1, 0); PG8_LDB(B1, 1, 1); PG8_SCHED; PG8_LDA(At, 1, 0); PG8_STAGE(PG8_SA(0, 1), a2 + hstepA, voffA);
;             PG8_WAIT_V(8); PG8_WAIT_L(0); PG8_BAR; PG8_MMA(0, 0, At, B0); PG8_MMA(0, 1, At, B1); PG8_BAR; PG8_SCHED;
;             if constexpr (!HALFU) PG8_LDA(At, 1, 1); PG8_STAGE(PG8_SB(1, 0), b3, voffB); PG8_STAGE(PG8_SB(1, 1), b3 + hstep, voffB); PG8_STAGE(PG8_SA(1, 0), a3, voffA);
;             PG8_WAIT_V(8); PG8_WAIT_L(0); PG8_BAR; if constexpr (!HALFU) { PG8_MMA(1, 0, At, B0); PG8_MMA(1, 1, At, B1); } PG8_BAR; PG8_SCHED;
	s_mov_b32 m0, s29
	s_nop 0
	global_load_lds_dwordx4 v252, s[38:39]
	s_mov_b32 m0, s41
	s_nop 0
	global_load_lds_dwordx4 v146, s[38:39]
	s_add_i32 s59, 0, 0x18000
	v_add_u32_e32 v8, s59, v154
	s_add_i32 s60, 0, 0x1c000
	s_nop 1
	ds_read_b128 v[0:3], v8
	ds_read_b128 v[4:7], v8 offset:1024
	ds_read_b128 v[16:19], v8 offset:2048
	ds_read_b128 v[20:23], v8 offset:3072
	v_add_u32_e32 v8, s60, v154
	ds_read_b128 v[128:131], v8
	ds_read_b128 v[132:135], v8 offset:1024
	ds_read_b128 v[164:167], v8 offset:2048
	ds_read_b128 v[168:171], v8 offset:3072
	s_add_u32 s14, s38, 0x80000
	s_addc_u32 s15, s39, 0
	s_mov_b32 m0, s42
	ds_read_b128 v[8:11], v157 offset:32768
	ds_read_b128 v[12:15], v157 offset:33792
	ds_read_b128 v[24:27], v157 offset:34816
	ds_read_b128 v[28:31], v157 offset:35840
	ds_read_b128 v[32:35], v157 offset:36864
	ds_read_b128 v[36:39], v157 offset:37888
	ds_read_b128 v[40:43], v157 offset:38912
	ds_read_b128 v[44:47], v157 offset:39936
	global_load_lds_dwordx4 v252, s[14:15]
	s_mov_b32 m0, s43
	s_nop 0
	global_load_lds_dwordx4 v146, s[14:15]
	s_waitcnt vmcnt(8)
	s_waitcnt lgkmcnt(0)
	s_barrier
	s_setprio 1
	s_waitcnt lgkmcnt(0)
	v_mfma_scale_f32_16x16x128_f8f6f4 v[124:127], v[0:7], v[8:15], v[124:127], v158, v158 op_sel_hi:[0,0,0]
	v_mfma_scale_f32_16x16x128_f8f6f4 v[120:123], v[16:23], v[8:15], v[120:123], v158, v158 op_sel_hi:[0,0,0]
	v_mfma_scale_f32_16x16x128_f8f6f4 v[108:111], v[0:7], v[24:31], v[108:111], v158, v158 op_sel_hi:[0,0,0]
	v_mfma_scale_f32_16x16x128_f8f6f4 v[104:107], v[16:23], v[24:31], v[104:107], v158, v158 op_sel_hi:[0,0,0]
	v_mfma_scale_f32_16x16x128_f8f6f4 v[92:95], v[0:7], v[32:39], v[136:139], v158, v158 op_sel_hi:[0,0,0]
	v_mfma_scale_f32_16x16x128_f8f6f4 v[88:91], v[16:23], v[32:39], v[220:223], v158, v158 op_sel_hi:[0,0,0]
	v_mfma_scale_f32_16x16x128_f8f6f4 v[76:79], v[0:7], v[40:47], v[224:227], v158, v158 op_sel_hi:[0,0,0]
	v_mfma_scale_f32_16x16x128_f8f6f4 v[72:75], v[16:23], v[40:47], v[228:231], v158, v158 op_sel_hi:[0,0,0]
	s_setprio 0
	s_setprio 1
	v_mfma_scale_f32_16x16x128_f8f6f4 v[116:119], v[128:135], v[8:15], v[116:119], v158, v158 op_sel_hi:[0,0,0]
	v_mfma_scale_f32_16x16x128_f8f6f4 v[112:115], v[164:171], v[8:15], v[112:115], v158, v158 op_sel_hi:[0,0,0]
	v_mfma_scale_f32_16x16x128_f8f6f4 v[100:103], v[128:135], v[24:31], v[100:103], v158, v158 op_sel_hi:[0,0,0]
	v_mfma_scale_f32_16x16x128_f8f6f4 v[96:99], v[164:171], v[24:31], v[96:99], v158, v158 op_sel_hi:[0,0,0]
	v_mfma_scale_f32_16x16x128_f8f6f4 v[84:87], v[128:135], v[32:39], v[188:191], v158, v158 op_sel_hi:[0,0,0]
	v_mfma_scale_f32_16x16x128_f8f6f4 v[80:83], v[164:171], v[32:39], v[192:195], v158, v158 op_sel_hi:[0,0,0]
	v_mfma_scale_f32_16x16x128_f8f6f4 v[68:71], v[128:135], v[40:47], v[196:199], v158, v158 op_sel_hi:[0,0,0]
	v_mfma_scale_f32_16x16x128_f8f6f4 v[64:67], v[164:171], v[40:47], v[200:203], v158, v158 op_sel_hi:[0,0,0]
	s_setprio 0
	s_barrier
	s_add_u32 s14, s36, 0x80
	s_addc_u32 s15, s37, 0
	s_add_i32 s38, s59, s40
	s_mov_b32 m0, s38
	ds_read_b128 v[32:35], v157 offset:49152
	ds_read_b128 v[36:39], v157 offset:50176
	ds_read_b128 v[172:175], v157 offset:51200
	ds_read_b128 v[176:179], v157 offset:52224
	ds_read_b128 v[180:183], v157 offset:53248
	ds_read_b128 v[184:187], v157 offset:54272
	ds_read_b128 v[188:191], v157 offset:55296
	ds_read_b128 v[192:195], v157 offset:56320
	global_load_lds_dwordx4 v144, s[14:15]
	s_add_i32 m0, s38, 0x2000
	v_lshl_add_u64 v[8:9], s[14:15], 0, v[148:149]
	s_add_u32 s14, s36, 0x80080
	s_addc_u32 s15, s37, 0
	s_add_i32 s36, s60, s40
	global_load_lds_dwordx4 v[8:9], off
	s_mov_b32 m0, s36
	s_nop 0
	global_load_lds_dwordx4 v144, s[14:15]
	s_add_i32 m0, s36, 0x2000
	s_nop 0
	global_load_lds_dwordx4 v148, s[14:15]
	s_waitcnt vmcnt(4)
	s_waitcnt lgkmcnt(0)
	s_barrier
	s_setprio 1
	s_waitcnt lgkmcnt(0)
	v_mfma_scale_f32_16x16x128_f8f6f4 v[60:63], v[0:7], v[32:39], v[60:63], v158, v158 op_sel_hi:[0,0,0]
	v_mfma_scale_f32_16x16x128_f8f6f4 v[56:59], v[16:23], v[32:39], v[56:59], v158, v158 op_sel_hi:[0,0,0]
	v_mfma_scale_f32_16x16x128_f8f6f4 v[44:47], v[0:7], v[172:179], v[204:207], v158, v158 op_sel_hi:[0,0,0]
	v_mfma_scale_f32_16x16x128_f8f6f4 v[40:43], v[16:23], v[172:179], v[208:211], v158, v158 op_sel_hi:[0,0,0]
	v_mfma_scale_f32_16x16x128_f8f6f4 v[28:31], v[0:7], v[180:187], v[212:215], v158, v158 op_sel_hi:[0,0,0]
	v_mfma_scale_f32_16x16x128_f8f6f4 v[24:27], v[16:23], v[180:187], v[216:219], v158, v158 op_sel_hi:[0,0,0]
	v_mfma_scale_f32_16x16x128_f8f6f4 v[12:15], v[0:7], v[188:195], v[232:235], v158, v158 op_sel_hi:[0,0,0]
	v_mfma_scale_f32_16x16x128_f8f6f4 v[8:11], v[16:23], v[188:195], v[236:239], v158, v158 op_sel_hi:[0,0,0]
	s_setprio 0
	s_setprio 1
	v_mfma_scale_f32_16x16x128_f8f6f4 v[52:55], v[128:135], v[32:39], v[52:55], v158, v158 op_sel_hi:[0,0,0]
	v_mfma_scale_f32_16x16x128_f8f6f4 v[48:51], v[164:171], v[32:39], v[48:51], v158, v158 op_sel_hi:[0,0,0]
	v_mfma_scale_f32_16x16x128_f8f6f4 v[36:39], v[128:135], v[172:179], v[240:243], v158, v158 op_sel_hi:[0,0,0]
	v_mfma_scale_f32_16x16x128_f8f6f4 v[32:35], v[164:171], v[172:179], v[244:247], v158, v158 op_sel_hi:[0,0,0]
	v_mfma_scale_f32_16x16x128_f8f6f4 v[20:23], v[128:135], v[180:187], v[248:251], v158, v158 op_sel_hi:[0,0,0]
	v_mfma_scale_f32_16x16x128_f8f6f4 v[16:19], v[164:171], v[180:187], v[150:153], v158, v158 op_sel_hi:[0,0,0]
	v_mfma_scale_f32_16x16x128_f8f6f4 v[4:7], v[128:135], v[188:195], v[160:163], v158, v158 op_sel_hi:[0,0,0]
	v_mfma_scale_f32_16x16x128_f8f6f4 v[0:3], v[164:171], v[188:195], v[140:143], v158, v158 op_sel_hi:[0,0,0]
	s_setprio 0
	s_barrier
	s_add_i32 s58, s58, 2
	s_add_u32 s56, s56, 0x100
	s_addc_u32 s57, s57, 0
	s_cmp_gt_u32 s58, 29
	s_mov_b64 s[14:15], s[30:31]
	s_cbranch_scc0 .LBB0_317
	s_and_b64 vcc, exec, s[16:17]
	s_cbranch_vccz .LBB0_320
	s_barrier

; #define PG8_WAIT_V(n) asm volatile("s_waitcnt vmcnt(" #n ")" ::: "memory")
; #define PG8_WAIT_L(n) asm volatile("s_waitcnt lgkmcnt(" #n ")" ::: "memory")
; #define PG8_BAR __builtin_amdgcn_s_barrier()
; #define PG8_SCHED __builtin_amdgcn_sched_barrier(0)
;     ...
;             PG8_LDB(B0, 0, 0); PG8_LDB(B1, 0, 1); PG8_SCHED; PG8_LDA(At, 0, 0); PG8_STAGE(PG8_SA(1, 1), a1 + hstepA, voffA);
;             PG8_WAIT_V(8); PG8_WAIT_L(0); PG8_BAR; PG8_MMA(0, 0, At, B0); PG8_MMA(0, 1, At, B1); PG8_BAR; PG8_SCHED;
;             if constexpr (!HALFU) PG8_LDA(At, 0, 1); PG8_STAGE(PG8_SB(0, 0), b2, voffB); PG8_STAGE(PG8_SB(0, 1), b2 + hstep, voffB); PG8_STAGE(PG8_SA(0, 0), a2, voffA);
;             PG8_WAIT_V(8); PG8_WAIT_L(0); PG8_BAR; if constexpr (!HALFU) { PG8_MMA(1, 0, At, B0); PG8_MMA(1, 1, At, B1); } PG8_BAR; PG8_SCHED;
.LBB0_542:
	s_add_u32 s98, s28, 0x80
	s_addc_u32 s99, s29, 0
	s_mov_b32 m0, s53
	s_nop 0
	global_load_lds_dwordx4 v128, s[98:99]
	s_mov_b32 m0, s54
	s_nop 0
	global_load_lds_dwordx4 v130, s[98:99]
	ds_read_b128 v[142:145], v137
	ds_read_b128 v[146:149], v137 offset:1024
	ds_read_b128 v[150:153], v137 offset:2048
	ds_read_b128 v[154:157], v137 offset:3072
	ds_read_b128 v[158:161], v138
	ds_read_b128 v[162:165], v138 offset:1024
	ds_read_b128 v[166:169], v138 offset:2048
	ds_read_b128 v[170:173], v138 offset:3072
	s_add_u32 s30, s28, 0x100
	s_addc_u32 s31, s29, 0
	s_cmp_eq_u32 s61, 12
	s_cselect_b32 s40, s57, s30
	s_cselect_b32 s41, s23, s31
	s_cselect_b32 s38, s58, s59
	s_cselect_b32 s39, s21, s60
	s_add_u32 s36, s40, 0x80
	s_addc_u32 s37, s41, 0
	s_add_u32 s28, s28, 0x40080
	s_addc_u32 s29, s29, 0
	s_add_i32 m0, s45, 0xc000
	ds_read_b128 v[174:177], v139
	ds_read_b128 v[178:181], v139 offset:1024
	ds_read_b128 v[182:185], v139 offset:2048
	ds_read_b128 v[186:189], v139 offset:3072
	ds_read_b128 v[190:193], v139 offset:4096
	ds_read_b128 v[194:197], v139 offset:5120
	ds_read_b128 v[198:201], v139 offset:6144
	ds_read_b128 v[202:205], v139 offset:7168
	global_load_lds_dwordx4 v128, s[28:29]
	s_add_i32 m0, s45, 0xe000
	s_nop 0
	global_load_lds_dwordx4 v130, s[28:29]
	s_waitcnt vmcnt(8)
	s_waitcnt lgkmcnt(0)
	s_barrier
	s_setprio 1
	s_waitcnt lgkmcnt(0)
	v_mfma_scale_f32_16x16x128_f8f6f4 v[124:127], v[142:149], v[174:181], v[124:127], v140, v140 op_sel_hi:[0,0,0]
	v_mfma_scale_f32_16x16x128_f8f6f4 v[120:123], v[150:157], v[174:181], v[120:123], v140, v140 op_sel_hi:[0,0,0]
	v_mfma_scale_f32_16x16x128_f8f6f4 v[108:111], v[142:149], v[182:189], v[108:111], v140, v140 op_sel_hi:[0,0,0]
	v_mfma_scale_f32_16x16x128_f8f6f4 v[104:107], v[150:157], v[182:189], v[104:107], v140, v140 op_sel_hi:[0,0,0]
	v_mfma_scale_f32_16x16x128_f8f6f4 v[96:99], v[142:149], v[190:197], v[96:99], v140, v140 op_sel_hi:[0,0,0]
	v_mfma_scale_f32_16x16x128_f8f6f4 v[206:209], v[150:157], v[190:197], v[88:91], v140, v140 op_sel_hi:[0,0,0]
	v_mfma_scale_f32_16x16x128_f8f6f4 v[210:213], v[142:149], v[198:205], v[80:83], v140, v140 op_sel_hi:[0,0,0]
	v_mfma_scale_f32_16x16x128_f8f6f4 v[214:217], v[150:157], v[198:205], v[72:75], v140, v140 op_sel_hi:[0,0,0]
	s_setprio 0
	s_setprio 1
	v_mfma_scale_f32_16x16x128_f8f6f4 v[116:119], v[158:165], v[174:181], v[116:119], v140, v140 op_sel_hi:[0,0,0]
	v_mfma_scale_f32_16x16x128_f8f6f4 v[112:115], v[166:173], v[174:181], v[112:115], v140, v140 op_sel_hi:[0,0,0]
	v_mfma_scale_f32_16x16x128_f8f6f4 v[100:103], v[158:165], v[182:189], v[100:103], v140, v140 op_sel_hi:[0,0,0]
	v_mfma_scale_f32_16x16x128_f8f6f4 v[174:177], v[166:173], v[182:189], v[92:95], v140, v140 op_sel_hi:[0,0,0]
	v_mfma_scale_f32_16x16x128_f8f6f4 v[178:181], v[158:165], v[190:197], v[84:87], v140, v140 op_sel_hi:[0,0,0]
	v_mfma_scale_f32_16x16x128_f8f6f4 v[182:185], v[166:173], v[190:197], v[76:79], v140, v140 op_sel_hi:[0,0,0]
	v_mfma_scale_f32_16x16x128_f8f6f4 v[186:189], v[158:165], v[198:205], v[68:71], v140, v140 op_sel_hi:[0,0,0]
	v_mfma_scale_f32_16x16x128_f8f6f4 v[190:193], v[166:173], v[198:205], v[64:67], v140, v140 op_sel_hi:[0,0,0]
	s_setprio 0
	s_barrier
	s_add_i32 s28, s55, s43
	s_mov_b32 m0, s28
	s_nop 1
	global_load_lds_dwordx4 v128, s[38:39]
	s_add_i32 m0, s28, 0x2000
	s_add_u32 s28, s38, 0x40000
	s_addc_u32 s29, s39, 0
	s_add_i32 s62, s56, s43
	global_load_lds_dwordx4 v130, s[38:39]
	s_mov_b32 m0, s62
	s_nop 0
	global_load_lds_dwordx4 v128, s[28:29]
	s_add_i32 m0, s62, 0x2000
	s_nop 0
	global_load_lds_dwordx4 v130, s[28:29]
	ds_read_b128 v[64:67], v139 offset:16384
	ds_read_b128 v[68:71], v139 offset:17408
	ds_read_b128 v[72:75], v139 offset:18432
	ds_read_b128 v[76:79], v139 offset:19456
	ds_read_b128 v[80:83], v139 offset:20480
	ds_read_b128 v[84:87], v139 offset:21504
	ds_read_b128 v[88:91], v139 offset:22528
	ds_read_b128 v[92:95], v139 offset:23552
	s_waitcnt vmcnt(4)
	s_waitcnt lgkmcnt(0)
	s_barrier
	s_setprio 1
	s_waitcnt lgkmcnt(0)
	v_mfma_scale_f32_16x16x128_f8f6f4 v[60:63], v[142:149], v[64:71], v[60:63], v140, v140 op_sel_hi:[0,0,0]
	v_mfma_scale_f32_16x16x128_f8f6f4 v[56:59], v[150:157], v[64:71], v[56:59], v140, v140 op_sel_hi:[0,0,0]
	v_mfma_scale_f32_16x16x128_f8f6f4 v[48:51], v[142:149], v[72:79], v[48:51], v140, v140 op_sel_hi:[0,0,0]
	v_mfma_scale_f32_16x16x128_f8f6f4 v[194:197], v[150:157], v[72:79], v[40:43], v140, v140 op_sel_hi:[0,0,0]
	v_mfma_scale_f32_16x16x128_f8f6f4 v[198:201], v[142:149], v[80:87], v[32:35], v140, v140 op_sel_hi:[0,0,0]
	v_mfma_scale_f32_16x16x128_f8f6f4 v[202:205], v[150:157], v[80:87], v[24:27], v140, v140 op_sel_hi:[0,0,0]
	v_mfma_scale_f32_16x16x128_f8f6f4 v[218:221], v[142:149], v[88:95], v[16:19], v140, v140 op_sel_hi:[0,0,0]
	v_mfma_scale_f32_16x16x128_f8f6f4 v[222:225], v[150:157], v[88:95], v[8:11], v140, v140 op_sel_hi:[0,0,0]
	s_setprio 0
	s_setprio 1
	v_mfma_scale_f32_16x16x128_f8f6f4 v[52:55], v[158:165], v[64:71], v[52:55], v140, v140 op_sel_hi:[0,0,0]
	v_mfma_scale_f32_16x16x128_f8f6f4 v[226:229], v[166:173], v[64:71], v[44:47], v140, v140 op_sel_hi:[0,0,0]
	v_mfma_scale_f32_16x16x128_f8f6f4 v[230:233], v[158:165], v[72:79], v[36:39], v140, v140 op_sel_hi:[0,0,0]
	v_mfma_scale_f32_16x16x128_f8f6f4 v[234:237], v[166:173], v[72:79], v[28:31], v140, v140 op_sel_hi:[0,0,0]
	v_mfma_scale_f32_16x16x128_f8f6f4 v[238:241], v[158:165], v[80:87], v[20:23], v140, v140 op_sel_hi:[0,0,0]
	v_mfma_scale_f32_16x16x128_f8f6f4 v[242:245], v[166:173], v[80:87], v[12:15], v140, v140 op_sel_hi:[0,0,0]
	v_mfma_scale_f32_16x16x128_f8f6f4 v[246:249], v[158:165], v[88:95], v[4:7], v140, v140 op_sel_hi:[0,0,0]
	v_mfma_scale_f32_16x16x128_f8f6f4 v[250:253], v[166:173], v[88:95], v[0:3], v140, v140 op_sel_hi:[0,0,0]
	s_setprio 0
	s_barrier
; #define PG8_WAIT_V(n) asm volatile("s_waitcnt vmcnt(" #n ")" ::: "memory")
; #define PG8_WAIT_L(n) asm volatile("s_waitcnt lgkmcnt(" #n ")" ::: "memory")
; #define PG8_BAR __builtin_amdgcn_s_barrier()
; #define PG8_SCHED __builtin_amdgcn_sched_barrier(0)
;     ...
;             PG8_LDB(B0, 1, 0); PG8_LDB(B1, 1, 1); PG8_SCHED; PG8_LDA(At, 1, 0); PG8_STAGE(PG8_SA(0, 1), a2 + hstepA, voffA);
;             PG8_WAIT_V(8); PG8_WAIT_L(0); PG8_BAR; PG8_MMA(0, 0, At, B0); PG8_MMA(0, 1, At, B1); PG8_BAR; PG8_SCHED;
;             if constexpr (!HALFU) PG8_LDA(At, 1, 1); PG8_STAGE(PG8_SB(1, 0), b3, voffB); PG8_STAGE(PG8_SB(1, 1), b3 + hstep, voffB); PG8_STAGE(PG8_SA(1, 0), a3, voffA);
;             PG8_WAIT_V(8); PG8_WAIT_L(0); PG8_BAR; if constexpr (!HALFU) { PG8_MMA(1, 0, At, B0); PG8_MMA(1, 1, At, B1); } PG8_BAR; PG8_SCHED;
	s_mov_b32 m0, s45
	s_nop 0
	global_load_lds_dwordx4 v128, s[40:41]
	s_mov_b32 m0, s46
	s_nop 0
	global_load_lds_dwordx4 v130, s[40:41]
	s_add_i32 s62, 0, 0x18000
	s_add_i32 s63, 0, 0x1c000
	s_nop 0
	v_add_u32_e32 v12, s62, v136
	v_add_u32_e32 v16, s63, v136
	ds_read_b128 v[0:3], v12
	ds_read_b128 v[4:7], v12 offset:1024
	ds_read_b128 v[8:11], v12 offset:2048
	ds_read_b128 v[12:15], v12 offset:3072
	ds_read_b128 v[142:145], v16
	ds_read_b128 v[146:149], v16 offset:1024
	ds_read_b128 v[150:153], v16 offset:2048
	ds_read_b128 v[154:157], v16 offset:3072
	s_add_u32 s28, s40, 0x40000
	s_addc_u32 s29, s41, 0
	s_mov_b32 m0, s47
	ds_read_b128 v[16:19], v139 offset:32768
	ds_read_b128 v[20:23], v139 offset:33792
	ds_read_b128 v[24:27], v139 offset:34816
	ds_read_b128 v[28:31], v139 offset:35840
	ds_read_b128 v[32:35], v139 offset:36864
	ds_read_b128 v[36:39], v139 offset:37888
	ds_read_b128 v[40:43], v139 offset:38912
	ds_read_b128 v[44:47], v139 offset:39936
	global_load_lds_dwordx4 v128, s[28:29]
	s_mov_b32 m0, s48
	s_nop 0
	global_load_lds_dwordx4 v130, s[28:29]
	s_waitcnt vmcnt(8)
	s_waitcnt lgkmcnt(0)
	s_barrier
	s_setprio 1
	s_waitcnt lgkmcnt(0)
	v_mfma_scale_f32_16x16x128_f8f6f4 v[124:127], v[0:7], v[16:23], v[124:127], v140, v140 op_sel_hi:[0,0,0]
	v_mfma_scale_f32_16x16x128_f8f6f4 v[120:123], v[8:15], v[16:23], v[120:123], v140, v140 op_sel_hi:[0,0,0]
	v_mfma_scale_f32_16x16x128_f8f6f4 v[108:111], v[0:7], v[24:31], v[108:111], v140, v140 op_sel_hi:[0,0,0]
	v_mfma_scale_f32_16x16x128_f8f6f4 v[104:107], v[8:15], v[24:31], v[104:107], v140, v140 op_sel_hi:[0,0,0]
	v_mfma_scale_f32_16x16x128_f8f6f4 v[96:99], v[0:7], v[32:39], v[96:99], v140, v140 op_sel_hi:[0,0,0]
	v_mfma_scale_f32_16x16x128_f8f6f4 v[88:91], v[8:15], v[32:39], v[206:209], v140, v140 op_sel_hi:[0,0,0]
	v_mfma_scale_f32_16x16x128_f8f6f4 v[80:83], v[0:7], v[40:47], v[210:213], v140, v140 op_sel_hi:[0,0,0]
	v_mfma_scale_f32_16x16x128_f8f6f4 v[72:75], v[8:15], v[40:47], v[214:217], v140, v140 op_sel_hi:[0,0,0]
	s_setprio 0
	s_setprio 1
	v_mfma_scale_f32_16x16x128_f8f6f4 v[116:119], v[142:149], v[16:23], v[116:119], v140, v140 op_sel_hi:[0,0,0]
	v_mfma_scale_f32_16x16x128_f8f6f4 v[112:115], v[150:157], v[16:23], v[112:115], v140, v140 op_sel_hi:[0,0,0]
	v_mfma_scale_f32_16x16x128_f8f6f4 v[100:103], v[142:149], v[24:31], v[100:103], v140, v140 op_sel_hi:[0,0,0]
	v_mfma_scale_f32_16x16x128_f8f6f4 v[92:95], v[150:157], v[24:31], v[174:177], v140, v140 op_sel_hi:[0,0,0]
	v_mfma_scale_f32_16x16x128_f8f6f4 v[84:87], v[142:149], v[32:39], v[178:181], v140, v140 op_sel_hi:[0,0,0]
	v_mfma_scale_f32_16x16x128_f8f6f4 v[76:79], v[150:157], v[32:39], v[182:185], v140, v140 op_sel_hi:[0,0,0]
	v_mfma_scale_f32_16x16x128_f8f6f4 v[68:71], v[142:149], v[40:47], v[186:189], v140, v140 op_sel_hi:[0,0,0]
	v_mfma_scale_f32_16x16x128_f8f6f4 v[64:67], v[150:157], v[40:47], v[190:193], v140, v140 op_sel_hi:[0,0,0]
	s_setprio 0
	s_barrier
	s_add_u32 s28, s38, 0x80
	s_addc_u32 s29, s39, 0
	s_add_i32 s40, s62, s43
	s_mov_b32 m0, s40
	ds_read_b128 v[158:161], v139 offset:49152
	ds_read_b128 v[162:165], v139 offset:50176
	ds_read_b128 v[166:169], v139 offset:51200
	ds_read_b128 v[170:173], v139 offset:52224
	ds_read_b128 v[174:177], v139 offset:53248
	ds_read_b128 v[178:181], v139 offset:54272
	ds_read_b128 v[182:185], v139 offset:55296
	ds_read_b128 v[186:189], v139 offset:56320
	global_load_lds_dwordx4 v128, s[28:29]
	s_add_i32 m0, s40, 0x2000
	v_lshl_add_u64 v[16:17], s[28:29], 0, v[130:131]
	s_add_u32 s28, s38, 0x40080
	s_addc_u32 s29, s39, 0
	s_add_i32 s38, s63, s43
	global_load_lds_dwordx4 v[16:17], off
	s_mov_b32 m0, s38
	s_nop 0
	global_load_lds_dwordx4 v128, s[28:29]
	s_add_i32 m0, s38, 0x2000
	s_nop 0
	global_load_lds_dwordx4 v130, s[28:29]
	s_waitcnt vmcnt(4)
	s_waitcnt lgkmcnt(0)
	s_barrier
	s_setprio 1
	s_waitcnt lgkmcnt(0)
	v_mfma_scale_f32_16x16x128_f8f6f4 v[60:63], v[0:7], v[158:165], v[60:63], v140, v140 op_sel_hi:[0,0,0]
	v_mfma_scale_f32_16x16x128_f8f6f4 v[56:59], v[8:15], v[158:165], v[56:59], v140, v140 op_sel_hi:[0,0,0]
	v_mfma_scale_f32_16x16x128_f8f6f4 v[48:51], v[0:7], v[166:173], v[48:51], v140, v140 op_sel_hi:[0,0,0]
	v_mfma_scale_f32_16x16x128_f8f6f4 v[40:43], v[8:15], v[166:173], v[194:197], v140, v140 op_sel_hi:[0,0,0]
	v_mfma_scale_f32_16x16x128_f8f6f4 v[32:35], v[0:7], v[174:181], v[198:201], v140, v140 op_sel_hi:[0,0,0]
	v_mfma_scale_f32_16x16x128_f8f6f4 v[24:27], v[8:15], v[174:181], v[202:205], v140, v140 op_sel_hi:[0,0,0]
	v_mfma_scale_f32_16x16x128_f8f6f4 v[16:19], v[0:7], v[182:189], v[218:221], v140, v140 op_sel_hi:[0,0,0]
	v_mfma_scale_f32_16x16x128_f8f6f4 v[8:11], v[8:15], v[182:189], v[222:225], v140, v140 op_sel_hi:[0,0,0]
	s_setprio 0
	s_setprio 1
	v_mfma_scale_f32_16x16x128_f8f6f4 v[52:55], v[142:149], v[158:165], v[52:55], v140, v140 op_sel_hi:[0,0,0]
	v_mfma_scale_f32_16x16x128_f8f6f4 v[44:47], v[150:157], v[158:165], v[226:229], v140, v140 op_sel_hi:[0,0,0]
	v_mfma_scale_f32_16x16x128_f8f6f4 v[36:39], v[142:149], v[166:173], v[230:233], v140, v140 op_sel_hi:[0,0,0]
	v_mfma_scale_f32_16x16x128_f8f6f4 v[28:31], v[150:157], v[166:173], v[234:237], v140, v140 op_sel_hi:[0,0,0]
	v_mfma_scale_f32_16x16x128_f8f6f4 v[20:23], v[142:149], v[174:181], v[238:241], v140, v140 op_sel_hi:[0,0,0]
	v_mfma_scale_f32_16x16x128_f8f6f4 v[12:15], v[150:157], v[174:181], v[242:245], v140, v140 op_sel_hi:[0,0,0]
	v_mfma_scale_f32_16x16x128_f8f6f4 v[4:7], v[142:149], v[182:189], v[246:249], v140, v140 op_sel_hi:[0,0,0]
	v_mfma_scale_f32_16x16x128_f8f6f4 v[0:3], v[150:157], v[182:189], v[250:253], v140, v140 op_sel_hi:[0,0,0]
	s_setprio 0
	s_barrier
	s_add_i32 s61, s61, 2
	s_add_u32 s59, s59, 0x100
	s_addc_u32 s60, s60, 0
	s_cmp_gt_u32 s61, 13
	s_mov_b64 s[28:29], s[30:31]
	s_cbranch_scc0 .LBB0_542
	s_and_b64 vcc, exec, s[6:7]
	s_cbranch_vccz .LBB0_545
	s_barrier

; #define PG8_WAIT_V(n) asm volatile("s_waitcnt vmcnt(" #n ")" ::: "memory")
; #define PG8_WAIT_L(n) asm volatile("s_waitcnt lgkmcnt(" #n ")" ::: "memory")
; #define PG8_BAR __builtin_amdgcn_s_barrier()
; #define PG8_SCHED __builtin_amdgcn_sched_barrier(0)
;     ...
;             PG8_LDB(B0, 0, 0); PG8_LDB(B1, 0, 1); PG8_SCHED; PG8_LDA(At, 0, 0); PG8_STAGE(PG8_SA(1, 1), a1 + hstepA, voffA);
;             PG8_WAIT_V(8); PG8_WAIT_L(0); PG8_BAR; PG8_MMA(0, 0, At, B0); PG8_MMA(0, 1, At, B1); PG8_BAR; PG8_SCHED;
;             if constexpr (!HALFU) PG8_LDA(At, 0, 1); PG8_STAGE(PG8_SB(0, 0), b2, voffB); PG8_STAGE(PG8_SB(0, 1), b2 + hstep, voffB); PG8_STAGE(PG8_SA(0, 0), a2, voffA);
;             PG8_WAIT_V(8); PG8_WAIT_L(0); PG8_BAR; if constexpr (!HALFU) { PG8_MMA(1, 0, At, B0); PG8_MMA(1, 1, At, B1); } PG8_BAR; PG8_SCHED;
.LBB0_670:
	s_add_u32 s98, s18, 0x80
	s_addc_u32 s99, s19, 0
	s_mov_b32 m0, s43
	s_nop 0
	global_load_lds_dwordx4 v134, s[98:99]
	s_mov_b32 m0, s44
	s_nop 0
	global_load_lds_dwordx4 v132, s[98:99]
	ds_read_b128 v[144:147], v141
	ds_read_b128 v[148:151], v141 offset:1024
	ds_read_b128 v[152:155], v141 offset:2048
	ds_read_b128 v[156:159], v141 offset:3072
	ds_read_b128 v[160:163], v142
	ds_read_b128 v[164:167], v142 offset:1024
	ds_read_b128 v[168:171], v142 offset:2048
	ds_read_b128 v[172:175], v142 offset:3072
	s_add_u32 s20, s18, 0x100
	s_addc_u32 s21, s19, 0
	s_cmp_eq_u32 s53, 60
	s_cselect_b32 s26, s49, s20
	s_cselect_b32 s27, s11, s21
	s_cselect_b32 s24, s50, s51
	s_cselect_b32 s25, s9, s52
	s_add_u32 s22, s26, 0x80
	s_addc_u32 s23, s27, 0
	s_add_u32 s18, s18, 0x100080
	s_addc_u32 s19, s19, 0
	s_add_i32 m0, s17, 0xc000
	ds_read_b128 v[176:179], v143
	ds_read_b128 v[180:183], v143 offset:1024
	ds_read_b128 v[184:187], v143 offset:2048
	ds_read_b128 v[188:191], v143 offset:3072
	ds_read_b128 v[192:195], v143 offset:4096
	ds_read_b128 v[196:199], v143 offset:5120
	ds_read_b128 v[200:203], v143 offset:6144
	ds_read_b128 v[204:207], v143 offset:7168
	global_load_lds_dwordx4 v134, s[18:19]
	s_add_i32 m0, s17, 0xe000
	s_nop 0
	global_load_lds_dwordx4 v132, s[18:19]
	s_waitcnt vmcnt(8)
	s_waitcnt lgkmcnt(0)
	s_barrier
	s_setprio 1
	s_waitcnt lgkmcnt(0)
	v_mfma_f32_16x16x32_bf16 v[124:127], v[144:147], v[176:179], v[124:127]
	v_mfma_f32_16x16x32_bf16 v[120:123], v[152:155], v[176:179], v[120:123]
	v_mfma_f32_16x16x32_bf16 v[108:111], v[144:147], v[184:187], v[108:111]
	v_mfma_f32_16x16x32_bf16 v[104:107], v[152:155], v[184:187], v[104:107]
	v_mfma_f32_16x16x32_bf16 v[92:95], v[144:147], v[192:195], v[92:95]
	v_mfma_f32_16x16x32_bf16 v[88:91], v[152:155], v[192:195], v[88:91]
	v_mfma_f32_16x16x32_bf16 v[76:79], v[144:147], v[200:203], v[76:79]
	v_mfma_f32_16x16x32_bf16 v[72:75], v[152:155], v[200:203], v[72:75]
	v_mfma_f32_16x16x32_bf16 v[124:127], v[148:151], v[180:183], v[124:127]
	v_mfma_f32_16x16x32_bf16 v[120:123], v[156:159], v[180:183], v[120:123]
	v_mfma_f32_16x16x32_bf16 v[108:111], v[148:151], v[188:191], v[108:111]
	v_mfma_f32_16x16x32_bf16 v[104:107], v[156:159], v[188:191], v[104:107]
	v_mfma_f32_16x16x32_bf16 v[92:95], v[148:151], v[196:199], v[92:95]
	v_mfma_f32_16x16x32_bf16 v[88:91], v[156:159], v[196:199], v[88:91]
	v_mfma_f32_16x16x32_bf16 v[76:79], v[148:151], v[204:207], v[76:79]
	v_mfma_f32_16x16x32_bf16 v[72:75], v[156:159], v[204:207], v[72:75]
	s_setprio 0
	s_setprio 1
	v_mfma_f32_16x16x32_bf16 v[116:119], v[160:163], v[176:179], v[116:119]
	v_mfma_f32_16x16x32_bf16 v[112:115], v[168:171], v[176:179], v[112:115]
	v_mfma_f32_16x16x32_bf16 v[100:103], v[160:163], v[184:187], v[100:103]
	v_mfma_f32_16x16x32_bf16 v[96:99], v[168:171], v[184:187], v[96:99]
	v_mfma_f32_16x16x32_bf16 v[84:87], v[160:163], v[192:195], v[84:87]
	v_mfma_f32_16x16x32_bf16 v[80:83], v[168:171], v[192:195], v[80:83]
	v_mfma_f32_16x16x32_bf16 v[68:71], v[160:163], v[200:203], v[68:71]
	v_mfma_f32_16x16x32_bf16 v[64:67], v[168:171], v[200:203], v[64:67]
	v_mfma_f32_16x16x32_bf16 v[116:119], v[164:167], v[180:183], v[116:119]
	v_mfma_f32_16x16x32_bf16 v[112:115], v[172:175], v[180:183], v[112:115]
	v_mfma_f32_16x16x32_bf16 v[100:103], v[164:167], v[188:191], v[100:103]
	v_mfma_f32_16x16x32_bf16 v[96:99], v[172:175], v[188:191], v[96:99]
	v_mfma_f32_16x16x32_bf16 v[84:87], v[164:167], v[196:199], v[84:87]
	v_mfma_f32_16x16x32_bf16 v[80:83], v[172:175], v[196:199], v[80:83]
	v_mfma_f32_16x16x32_bf16 v[68:71], v[164:167], v[204:207], v[68:71]
	v_mfma_f32_16x16x32_bf16 v[64:67], v[172:175], v[204:207], v[64:67]
	s_setprio 0
	s_barrier
	s_add_i32 s18, s45, s30
	s_mov_b32 m0, s18
	s_nop 0
	global_load_lds_dwordx4 v128, s[24:25]
	s_add_i32 m0, s18, 0x2000
	s_add_u32 s18, s24, 0x100000
	s_addc_u32 s19, s25, 0
	s_add_i32 s54, s46, s30
	global_load_lds_dwordx4 v130, s[24:25]
	s_mov_b32 m0, s54
	s_nop 0
	global_load_lds_dwordx4 v128, s[18:19]
	s_add_i32 m0, s54, 0x2000
	s_nop 0
	global_load_lds_dwordx4 v130, s[18:19]
	ds_read_b128 v[176:179], v143 offset:16384
	ds_read_b128 v[180:183], v143 offset:17408
	ds_read_b128 v[184:187], v143 offset:18432
	ds_read_b128 v[188:191], v143 offset:19456
	ds_read_b128 v[192:195], v143 offset:20480
	ds_read_b128 v[196:199], v143 offset:21504
	ds_read_b128 v[200:203], v143 offset:22528
	ds_read_b128 v[204:207], v143 offset:23552
	s_waitcnt vmcnt(4)
	s_waitcnt lgkmcnt(0)
	s_barrier
	s_setprio 1
	s_waitcnt lgkmcnt(0)
	v_mfma_f32_16x16x32_bf16 v[60:63], v[144:147], v[176:179], v[60:63]
	v_mfma_f32_16x16x32_bf16 v[56:59], v[152:155], v[176:179], v[56:59]
	v_mfma_f32_16x16x32_bf16 v[44:47], v[144:147], v[184:187], v[44:47]
	v_mfma_f32_16x16x32_bf16 v[40:43], v[152:155], v[184:187], v[40:43]
	v_mfma_f32_16x16x32_bf16 v[28:31], v[144:147], v[192:195], v[28:31]
	v_mfma_f32_16x16x32_bf16 v[24:27], v[152:155], v[192:195], v[24:27]
	v_mfma_f32_16x16x32_bf16 v[12:15], v[144:147], v[200:203], v[12:15]
	v_mfma_f32_16x16x32_bf16 v[8:11], v[152:155], v[200:203], v[8:11]
	v_mfma_f32_16x16x32_bf16 v[60:63], v[148:151], v[180:183], v[60:63]
	v_mfma_f32_16x16x32_bf16 v[56:59], v[156:159], v[180:183], v[56:59]
	v_mfma_f32_16x16x32_bf16 v[44:47], v[148:151], v[188:191], v[44:47]
	v_mfma_f32_16x16x32_bf16 v[40:43], v[156:159], v[188:191], v[40:43]
	v_mfma_f32_16x16x32_bf16 v[28:31], v[148:151], v[196:199], v[28:31]
	v_mfma_f32_16x16x32_bf16 v[24:27], v[156:159], v[196:199], v[24:27]
	v_mfma_f32_16x16x32_bf16 v[12:15], v[148:151], v[204:207], v[12:15]
	v_mfma_f32_16x16x32_bf16 v[8:11], v[156:159], v[204:207], v[8:11]
	s_setprio 0
	s_setprio 1
	v_mfma_f32_16x16x32_bf16 v[52:55], v[160:163], v[176:179], v[52:55]
	v_mfma_f32_16x16x32_bf16 v[48:51], v[168:171], v[176:179], v[48:51]
	v_mfma_f32_16x16x32_bf16 v[36:39], v[160:163], v[184:187], v[36:39]
	v_mfma_f32_16x16x32_bf16 v[32:35], v[168:171], v[184:187], v[32:35]
	v_mfma_f32_16x16x32_bf16 v[20:23], v[160:163], v[192:195], v[20:23]
	v_mfma_f32_16x16x32_bf16 v[16:19], v[168:171], v[192:195], v[16:19]
	v_mfma_f32_16x16x32_bf16 v[4:7], v[160:163], v[200:203], v[4:7]
	v_mfma_f32_16x16x32_bf16 v[0:3], v[168:171], v[200:203], v[0:3]
	v_mfma_f32_16x16x32_bf16 v[52:55], v[164:167], v[180:183], v[52:55]
	v_mfma_f32_16x16x32_bf16 v[48:51], v[172:175], v[180:183], v[48:51]
	v_mfma_f32_16x16x32_bf16 v[36:39], v[164:167], v[188:191], v[36:39]
	v_mfma_f32_16x16x32_bf16 v[32:35], v[172:175], v[188:191], v[32:35]
	v_mfma_f32_16x16x32_bf16 v[20:23], v[164:167], v[196:199], v[20:23]
	v_mfma_f32_16x16x32_bf16 v[16:19], v[172:175], v[196:199], v[16:19]
	v_mfma_f32_16x16x32_bf16 v[4:7], v[164:167], v[204:207], v[4:7]
	v_mfma_f32_16x16x32_bf16 v[0:3], v[172:175], v[204:207], v[0:3]
	s_setprio 0
	s_barrier
; #define PG8_WAIT_V(n) asm volatile("s_waitcnt vmcnt(" #n ")" ::: "memory")
; #define PG8_WAIT_L(n) asm volatile("s_waitcnt lgkmcnt(" #n ")" ::: "memory")
; #define PG8_BAR __builtin_amdgcn_s_barrier()
; #define PG8_SCHED __builtin_amdgcn_sched_barrier(0)
;     ...
;             PG8_LDB(B0, 1, 0); PG8_LDB(B1, 1, 1); PG8_SCHED; PG8_LDA(At, 1, 0); PG8_STAGE(PG8_SA(0, 1), a2 + hstepA, voffA);
;             PG8_WAIT_V(8); PG8_WAIT_L(0); PG8_BAR; PG8_MMA(0, 0, At, B0); PG8_MMA(0, 1, At, B1); PG8_BAR; PG8_SCHED;
;             if constexpr (!HALFU) PG8_LDA(At, 1, 1); PG8_STAGE(PG8_SB(1, 0), b3, voffB); PG8_STAGE(PG8_SB(1, 1), b3 + hstep, voffB); PG8_STAGE(PG8_SA(1, 0), a3, voffA);
;             PG8_WAIT_V(8); PG8_WAIT_L(0); PG8_BAR; if constexpr (!HALFU) { PG8_MMA(1, 0, At, B0); PG8_MMA(1, 1, At, B1); } PG8_BAR; PG8_SCHED;
	s_mov_b32 m0, s17
	s_nop 0
	global_load_lds_dwordx4 v134, s[26:27]
	s_mov_b32 m0, s36
	s_nop 0
	global_load_lds_dwordx4 v132, s[26:27]
	s_add_i32 s54, 0, 0x18000
	s_add_i32 s55, 0, 0x1c000
	v_add_u32_e32 v156, s54, v140
	v_add_u32_e32 v172, s55, v140
	ds_read_b128 v[144:147], v156
	ds_read_b128 v[148:151], v156 offset:1024
	ds_read_b128 v[152:155], v156 offset:2048
	ds_read_b128 v[156:159], v156 offset:3072
	ds_read_b128 v[160:163], v172
	ds_read_b128 v[164:167], v172 offset:1024
	ds_read_b128 v[168:171], v172 offset:2048
	ds_read_b128 v[172:175], v172 offset:3072
	s_add_u32 s18, s26, 0x100000
	s_addc_u32 s19, s27, 0
	s_mov_b32 m0, s37
	ds_read_b128 v[176:179], v143 offset:32768
	ds_read_b128 v[180:183], v143 offset:33792
	ds_read_b128 v[184:187], v143 offset:34816
	ds_read_b128 v[188:191], v143 offset:35840
	ds_read_b128 v[192:195], v143 offset:36864
	ds_read_b128 v[196:199], v143 offset:37888
	ds_read_b128 v[200:203], v143 offset:38912
	ds_read_b128 v[204:207], v143 offset:39936
	global_load_lds_dwordx4 v134, s[18:19]
	s_mov_b32 m0, s38
	s_nop 0
	global_load_lds_dwordx4 v132, s[18:19]
	s_waitcnt vmcnt(8)
	s_waitcnt lgkmcnt(0)
	s_barrier
	s_setprio 1
	s_waitcnt lgkmcnt(0)
	v_mfma_f32_16x16x32_bf16 v[124:127], v[144:147], v[176:179], v[124:127]
	v_mfma_f32_16x16x32_bf16 v[120:123], v[152:155], v[176:179], v[120:123]
	v_mfma_f32_16x16x32_bf16 v[108:111], v[144:147], v[184:187], v[108:111]
	v_mfma_f32_16x16x32_bf16 v[104:107], v[152:155], v[184:187], v[104:107]
	v_mfma_f32_16x16x32_bf16 v[92:95], v[144:147], v[192:195], v[92:95]
	v_mfma_f32_16x16x32_bf16 v[88:91], v[152:155], v[192:195], v[88:91]
	v_mfma_f32_16x16x32_bf16 v[76:79], v[144:147], v[200:203], v[76:79]
	v_mfma_f32_16x16x32_bf16 v[72:75], v[152:155], v[200:203], v[72:75]
	v_mfma_f32_16x16x32_bf16 v[124:127], v[148:151], v[180:183], v[124:127]
	v_mfma_f32_16x16x32_bf16 v[120:123], v[156:159], v[180:183], v[120:123]
	v_mfma_f32_16x16x32_bf16 v[108:111], v[148:151], v[188:191], v[108:111]
	v_mfma_f32_16x16x32_bf16 v[104:107], v[156:159], v[188:191], v[104:107]
	v_mfma_f32_16x16x32_bf16 v[92:95], v[148:151], v[196:199], v[92:95]
	v_mfma_f32_16x16x32_bf16 v[88:91], v[156:159], v[196:199], v[88:91]
	v_mfma_f32_16x16x32_bf16 v[76:79], v[148:151], v[204:207], v[76:79]
	v_mfma_f32_16x16x32_bf16 v[72:75], v[156:159], v[204:207], v[72:75]
	s_setprio 0
	s_setprio 1
	v_mfma_f32_16x16x32_bf16 v[116:119], v[160:163], v[176:179], v[116:119]
	v_mfma_f32_16x16x32_bf16 v[112:115], v[168:171], v[176:179], v[112:115]
	v_mfma_f32_16x16x32_bf16 v[100:103], v[160:163], v[184:187], v[100:103]
	v_mfma_f32_16x16x32_bf16 v[96:99], v[168:171], v[184:187], v[96:99]
	v_mfma_f32_16x16x32_bf16 v[84:87], v[160:163], v[192:195], v[84:87]
	v_mfma_f32_16x16x32_bf16 v[80:83], v[168:171], v[192:195], v[80:83]
	v_mfma_f32_16x16x32_bf16 v[68:71], v[160:163], v[200:203], v[68:71]
	v_mfma_f32_16x16x32_bf16 v[64:67], v[168:171], v[200:203], v[64:67]
	v_mfma_f32_16x16x32_bf16 v[116:119], v[164:167], v[180:183], v[116:119]
	v_mfma_f32_16x16x32_bf16 v[112:115], v[172:175], v[180:183], v[112:115]
	v_mfma_f32_16x16x32_bf16 v[100:103], v[164:167], v[188:191], v[100:103]
	v_mfma_f32_16x16x32_bf16 v[96:99], v[172:175], v[188:191], v[96:99]
	v_mfma_f32_16x16x32_bf16 v[84:87], v[164:167], v[196:199], v[84:87]
	v_mfma_f32_16x16x32_bf16 v[80:83], v[172:175], v[196:199], v[80:83]
	v_mfma_f32_16x16x32_bf16 v[68:71], v[164:167], v[204:207], v[68:71]
	v_mfma_f32_16x16x32_bf16 v[64:67], v[172:175], v[204:207], v[64:67]
	s_setprio 0
	s_barrier
	s_add_u32 s18, s24, 0x80
	s_addc_u32 s19, s25, 0
	s_add_i32 s26, s54, s30
	s_mov_b32 m0, s26
	ds_read_b128 v[176:179], v143 offset:49152
	ds_read_b128 v[180:183], v143 offset:50176
	ds_read_b128 v[184:187], v143 offset:51200
	ds_read_b128 v[188:191], v143 offset:52224
	ds_read_b128 v[192:195], v143 offset:53248
	ds_read_b128 v[196:199], v143 offset:54272
	ds_read_b128 v[200:203], v143 offset:55296
	ds_read_b128 v[204:207], v143 offset:56320
	global_load_lds_dwordx4 v128, s[18:19]
	s_add_i32 m0, s26, 0x2000
	v_lshl_add_u64 v[208:209], s[18:19], 0, v[130:131]
	s_add_u32 s18, s24, 0x100080
	s_addc_u32 s19, s25, 0
	s_add_i32 s24, s55, s30
	global_load_lds_dwordx4 v[208:209], off
	s_mov_b32 m0, s24
	s_nop 0
	global_load_lds_dwordx4 v128, s[18:19]
	s_add_i32 m0, s24, 0x2000
	s_nop 0
	global_load_lds_dwordx4 v130, s[18:19]
	s_waitcnt vmcnt(4)
	s_waitcnt lgkmcnt(0)
	s_barrier
	s_setprio 1
	s_waitcnt lgkmcnt(0)
	v_mfma_f32_16x16x32_bf16 v[60:63], v[144:147], v[176:179], v[60:63]
	v_mfma_f32_16x16x32_bf16 v[56:59], v[152:155], v[176:179], v[56:59]
	v_mfma_f32_16x16x32_bf16 v[44:47], v[144:147], v[184:187], v[44:47]
	v_mfma_f32_16x16x32_bf16 v[40:43], v[152:155], v[184:187], v[40:43]
	v_mfma_f32_16x16x32_bf16 v[28:31], v[144:147], v[192:195], v[28:31]
	v_mfma_f32_16x16x32_bf16 v[24:27], v[152:155], v[192:195], v[24:27]
	v_mfma_f32_16x16x32_bf16 v[12:15], v[144:147], v[200:203], v[12:15]
	v_mfma_f32_16x16x32_bf16 v[8:11], v[152:155], v[200:203], v[8:11]
	v_mfma_f32_16x16x32_bf16 v[60:63], v[148:151], v[180:183], v[60:63]
	v_mfma_f32_16x16x32_bf16 v[56:59], v[156:159], v[180:183], v[56:59]
	v_mfma_f32_16x16x32_bf16 v[44:47], v[148:151], v[188:191], v[44:47]
	v_mfma_f32_16x16x32_bf16 v[40:43], v[156:159], v[188:191], v[40:43]
	v_mfma_f32_16x16x32_bf16 v[28:31], v[148:151], v[196:199], v[28:31]
	v_mfma_f32_16x16x32_bf16 v[24:27], v[156:159], v[196:199], v[24:27]
	v_mfma_f32_16x16x32_bf16 v[12:15], v[148:151], v[204:207], v[12:15]
	v_mfma_f32_16x16x32_bf16 v[8:11], v[156:159], v[204:207], v[8:11]
	s_setprio 0
	s_setprio 1
	v_mfma_f32_16x16x32_bf16 v[52:55], v[160:163], v[176:179], v[52:55]
	v_mfma_f32_16x16x32_bf16 v[48:51], v[168:171], v[176:179], v[48:51]
	v_mfma_f32_16x16x32_bf16 v[36:39], v[160:163], v[184:187], v[36:39]
	v_mfma_f32_16x16x32_bf16 v[32:35], v[168:171], v[184:187], v[32:35]
	v_mfma_f32_16x16x32_bf16 v[20:23], v[160:163], v[192:195], v[20:23]
	v_mfma_f32_16x16x32_bf16 v[16:19], v[168:171], v[192:195], v[16:19]
	v_mfma_f32_16x16x32_bf16 v[4:7], v[160:163], v[200:203], v[4:7]
	v_mfma_f32_16x16x32_bf16 v[0:3], v[168:171], v[200:203], v[0:3]
	v_mfma_f32_16x16x32_bf16 v[52:55], v[164:167], v[180:183], v[52:55]
	v_mfma_f32_16x16x32_bf16 v[48:51], v[172:175], v[180:183], v[48:51]
	v_mfma_f32_16x16x32_bf16 v[36:39], v[164:167], v[188:191], v[36:39]
	v_mfma_f32_16x16x32_bf16 v[32:35], v[172:175], v[188:191], v[32:35]
	v_mfma_f32_16x16x32_bf16 v[20:23], v[164:167], v[196:199], v[20:23]
	v_mfma_f32_16x16x32_bf16 v[16:19], v[172:175], v[196:199], v[16:19]
	v_mfma_f32_16x16x32_bf16 v[4:7], v[164:167], v[204:207], v[4:7]
	v_mfma_f32_16x16x32_bf16 v[0:3], v[172:175], v[204:207], v[0:3]
	s_setprio 0
	s_barrier
	s_add_i32 s53, s53, 2
	s_add_u32 s51, s51, 0x100
	s_addc_u32 s52, s52, 0
	s_cmp_gt_u32 s53, 61
	s_mov_b64 s[18:19], s[20:21]
	s_cbranch_scc0 .LBB0_670
	s_and_b64 vcc, exec, s[6:7]
	s_cbranch_vccz .LBB0_673
	s_barrier

; #define PG8_WAIT_V(n) asm volatile("s_waitcnt vmcnt(" #n ")" ::: "memory")
; #define PG8_WAIT_L(n) asm volatile("s_waitcnt lgkmcnt(" #n ")" ::: "memory")
; #define PG8_BAR __builtin_amdgcn_s_barrier()
; #define PG8_SCHED __builtin_amdgcn_sched_barrier(0)
;     ...
;             PG8_LDB(B0, 0, 0); PG8_LDB(B1, 0, 1); PG8_SCHED; PG8_LDA(At, 0, 0); PG8_STAGE(PG8_SA(1, 1), a1 + hstepA, voffA);
;             PG8_WAIT_V(8); PG8_WAIT_L(0); PG8_BAR; PG8_MMA(0, 0, At, B0); PG8_MMA(0, 1, At, B1); PG8_BAR; PG8_SCHED;
;             if constexpr (!HALFU) PG8_LDA(At, 0, 1); PG8_STAGE(PG8_SB(0, 0), b2, voffB); PG8_STAGE(PG8_SB(0, 1), b2 + hstep, voffB); PG8_STAGE(PG8_SA(0, 0), a2, voffA);
;             PG8_WAIT_V(8); PG8_WAIT_L(0); PG8_BAR; if constexpr (!HALFU) { PG8_MMA(1, 0, At, B0); PG8_MMA(1, 1, At, B1); } PG8_BAR; PG8_SCHED;
.LBB0_793:
	s_add_u32 s98, s10, 0x80
	s_addc_u32 s99, s11, 0
	s_mov_b32 m0, s43
	s_nop 0
	global_load_lds_dwordx4 v128, s[98:99]
	s_mov_b32 m0, s44
	s_nop 0
	global_load_lds_dwordx4 v130, s[98:99]
	ds_read_b128 v[140:143], v137
	ds_read_b128 v[144:147], v137 offset:1024
	ds_read_b128 v[148:151], v137 offset:2048
	ds_read_b128 v[152:155], v137 offset:3072
	ds_read_b128 v[156:159], v138
	ds_read_b128 v[160:163], v138 offset:1024
	ds_read_b128 v[164:167], v138 offset:2048
	ds_read_b128 v[168:171], v138 offset:3072
	s_add_u32 s22, s10, 0x100
	s_addc_u32 s23, s11, 0
	s_cmpk_eq_i32 s54, 0xa8
	s_cselect_b32 s28, s6, s22
	s_cselect_b32 s29, s7, s23
	s_cselect_b32 s26, s20, s52
	s_cselect_b32 s27, s21, s53
	s_add_u32 s24, s28, 0x80
	s_addc_u32 s25, s29, 0
	s_add_u32 s10, s10, 0x2b0080
	s_addc_u32 s11, s11, 0
	s_add_i32 m0, s36, 0xc000
	ds_read_b128 v[172:175], v139
	ds_read_b128 v[176:179], v139 offset:1024
	ds_read_b128 v[180:183], v139 offset:2048
	ds_read_b128 v[184:187], v139 offset:3072
	ds_read_b128 v[188:191], v139 offset:4096
	ds_read_b128 v[192:195], v139 offset:5120
	ds_read_b128 v[196:199], v139 offset:6144
	ds_read_b128 v[200:203], v139 offset:7168
	global_load_lds_dwordx4 v128, s[10:11]
	s_add_i32 m0, s36, 0xe000
	s_nop 0
	global_load_lds_dwordx4 v130, s[10:11]
	s_waitcnt vmcnt(8)
	s_waitcnt lgkmcnt(0)
	s_barrier
	s_setprio 1
	s_waitcnt lgkmcnt(0)
	v_mfma_f32_16x16x32_bf16 v[124:127], v[140:143], v[172:175], v[124:127]
	v_mfma_f32_16x16x32_bf16 v[120:123], v[148:151], v[172:175], v[120:123]
	v_mfma_f32_16x16x32_bf16 v[112:115], v[140:143], v[180:183], v[112:115]
	v_mfma_f32_16x16x32_bf16 v[104:107], v[148:151], v[180:183], v[104:107]
	v_mfma_f32_16x16x32_bf16 v[96:99], v[140:143], v[188:191], v[96:99]
	v_mfma_f32_16x16x32_bf16 v[88:91], v[148:151], v[188:191], v[88:91]
	v_mfma_f32_16x16x32_bf16 v[80:83], v[140:143], v[196:199], v[80:83]
	v_mfma_f32_16x16x32_bf16 v[72:75], v[148:151], v[196:199], v[72:75]
	v_mfma_f32_16x16x32_bf16 v[124:127], v[144:147], v[176:179], v[124:127]
	v_mfma_f32_16x16x32_bf16 v[120:123], v[152:155], v[176:179], v[120:123]
	v_mfma_f32_16x16x32_bf16 v[112:115], v[144:147], v[184:187], v[112:115]
	v_mfma_f32_16x16x32_bf16 v[104:107], v[152:155], v[184:187], v[104:107]
	v_mfma_f32_16x16x32_bf16 v[96:99], v[144:147], v[192:195], v[96:99]
	v_mfma_f32_16x16x32_bf16 v[88:91], v[152:155], v[192:195], v[88:91]
	v_mfma_f32_16x16x32_bf16 v[80:83], v[144:147], v[200:203], v[80:83]
	v_mfma_f32_16x16x32_bf16 v[72:75], v[152:155], v[200:203], v[72:75]
	s_setprio 0
	s_setprio 1
	v_mfma_f32_16x16x32_bf16 v[116:119], v[156:159], v[172:175], v[116:119]
	v_mfma_f32_16x16x32_bf16 v[108:111], v[164:167], v[172:175], v[108:111]
	v_mfma_f32_16x16x32_bf16 v[100:103], v[156:159], v[180:183], v[100:103]
	v_mfma_f32_16x16x32_bf16 v[92:95], v[164:167], v[180:183], v[92:95]
	v_mfma_f32_16x16x32_bf16 v[84:87], v[156:159], v[188:191], v[84:87]
	v_mfma_f32_16x16x32_bf16 v[76:79], v[164:167], v[188:191], v[76:79]
	v_mfma_f32_16x16x32_bf16 v[68:71], v[156:159], v[196:199], v[68:71]
	v_mfma_f32_16x16x32_bf16 v[64:67], v[164:167], v[196:199], v[64:67]
	v_mfma_f32_16x16x32_bf16 v[116:119], v[160:163], v[176:179], v[116:119]
	v_mfma_f32_16x16x32_bf16 v[108:111], v[168:171], v[176:179], v[108:111]
	v_mfma_f32_16x16x32_bf16 v[100:103], v[160:163], v[184:187], v[100:103]
	v_mfma_f32_16x16x32_bf16 v[92:95], v[168:171], v[184:187], v[92:95]
	v_mfma_f32_16x16x32_bf16 v[84:87], v[160:163], v[192:195], v[84:87]
	v_mfma_f32_16x16x32_bf16 v[76:79], v[168:171], v[192:195], v[76:79]
	v_mfma_f32_16x16x32_bf16 v[68:71], v[160:163], v[200:203], v[68:71]
	v_mfma_f32_16x16x32_bf16 v[64:67], v[168:171], v[200:203], v[64:67]
	s_setprio 0
	s_barrier
	s_add_i32 s10, s46, s31
	s_mov_b32 m0, s10
	s_nop 0
	global_load_lds_dwordx4 v128, s[26:27]
	s_add_i32 m0, s10, 0x2000
	s_add_u32 s10, s26, 0x2b0000
	s_addc_u32 s11, s27, 0
	s_add_i32 s55, s47, s31
	global_load_lds_dwordx4 v130, s[26:27]
	s_mov_b32 m0, s55
	s_nop 0
	global_load_lds_dwordx4 v128, s[10:11]
	s_add_i32 m0, s55, 0x2000
	s_nop 0
	global_load_lds_dwordx4 v130, s[10:11]
	ds_read_b128 v[172:175], v139 offset:16384
	ds_read_b128 v[176:179], v139 offset:17408
	ds_read_b128 v[180:183], v139 offset:18432
	ds_read_b128 v[184:187], v139 offset:19456
	ds_read_b128 v[188:191], v139 offset:20480
	ds_read_b128 v[192:195], v139 offset:21504
	ds_read_b128 v[196:199], v139 offset:22528
	ds_read_b128 v[200:203], v139 offset:23552
	s_waitcnt vmcnt(4)
	s_waitcnt lgkmcnt(0)
	s_barrier
	s_setprio 1
	s_waitcnt lgkmcnt(0)
	v_mfma_f32_16x16x32_bf16 v[60:63], v[140:143], v[172:175], v[60:63]
	v_mfma_f32_16x16x32_bf16 v[56:59], v[148:151], v[172:175], v[56:59]
	v_mfma_f32_16x16x32_bf16 v[48:51], v[140:143], v[180:183], v[48:51]
	v_mfma_f32_16x16x32_bf16 v[40:43], v[148:151], v[180:183], v[40:43]
	v_mfma_f32_16x16x32_bf16 v[32:35], v[140:143], v[188:191], v[32:35]
	v_mfma_f32_16x16x32_bf16 v[24:27], v[148:151], v[188:191], v[24:27]
	v_mfma_f32_16x16x32_bf16 v[16:19], v[140:143], v[196:199], v[16:19]
	v_mfma_f32_16x16x32_bf16 v[8:11], v[148:151], v[196:199], v[8:11]
	v_mfma_f32_16x16x32_bf16 v[60:63], v[144:147], v[176:179], v[60:63]
	v_mfma_f32_16x16x32_bf16 v[56:59], v[152:155], v[176:179], v[56:59]
	v_mfma_f32_16x16x32_bf16 v[48:51], v[144:147], v[184:187], v[48:51]
	v_mfma_f32_16x16x32_bf16 v[40:43], v[152:155], v[184:187], v[40:43]
	v_mfma_f32_16x16x32_bf16 v[32:35], v[144:147], v[192:195], v[32:35]
	v_mfma_f32_16x16x32_bf16 v[24:27], v[152:155], v[192:195], v[24:27]
	v_mfma_f32_16x16x32_bf16 v[16:19], v[144:147], v[200:203], v[16:19]
	v_mfma_f32_16x16x32_bf16 v[8:11], v[152:155], v[200:203], v[8:11]
	s_setprio 0
	s_setprio 1
	v_mfma_f32_16x16x32_bf16 v[52:55], v[156:159], v[172:175], v[52:55]
	v_mfma_f32_16x16x32_bf16 v[44:47], v[164:167], v[172:175], v[44:47]
	v_mfma_f32_16x16x32_bf16 v[36:39], v[156:159], v[180:183], v[36:39]
	v_mfma_f32_16x16x32_bf16 v[28:31], v[164:167], v[180:183], v[28:31]
	v_mfma_f32_16x16x32_bf16 v[20:23], v[156:159], v[188:191], v[20:23]
	v_mfma_f32_16x16x32_bf16 v[12:15], v[164:167], v[188:191], v[12:15]
	v_mfma_f32_16x16x32_bf16 v[4:7], v[156:159], v[196:199], v[4:7]
	v_mfma_f32_16x16x32_bf16 v[0:3], v[164:167], v[196:199], v[0:3]
	v_mfma_f32_16x16x32_bf16 v[52:55], v[160:163], v[176:179], v[52:55]
	v_mfma_f32_16x16x32_bf16 v[44:47], v[168:171], v[176:179], v[44:47]
	v_mfma_f32_16x16x32_bf16 v[36:39], v[160:163], v[184:187], v[36:39]
	v_mfma_f32_16x16x32_bf16 v[28:31], v[168:171], v[184:187], v[28:31]
	v_mfma_f32_16x16x32_bf16 v[20:23], v[160:163], v[192:195], v[20:23]
	v_mfma_f32_16x16x32_bf16 v[12:15], v[168:171], v[192:195], v[12:15]
	v_mfma_f32_16x16x32_bf16 v[4:7], v[160:163], v[200:203], v[4:7]
	v_mfma_f32_16x16x32_bf16 v[0:3], v[168:171], v[200:203], v[0:3]
	s_setprio 0
	s_barrier
; #define PG8_WAIT_V(n) asm volatile("s_waitcnt vmcnt(" #n ")" ::: "memory")
; #define PG8_WAIT_L(n) asm volatile("s_waitcnt lgkmcnt(" #n ")" ::: "memory")
; #define PG8_BAR __builtin_amdgcn_s_barrier()
; #define PG8_SCHED __builtin_amdgcn_sched_barrier(0)
;     ...
;             PG8_LDB(B0, 1, 0); PG8_LDB(B1, 1, 1); PG8_SCHED; PG8_LDA(At, 1, 0); PG8_STAGE(PG8_SA(0, 1), a2 + hstepA, voffA);
;             PG8_WAIT_V(8); PG8_WAIT_L(0); PG8_BAR; PG8_MMA(0, 0, At, B0); PG8_MMA(0, 1, At, B1); PG8_BAR; PG8_SCHED;
;             if constexpr (!HALFU) PG8_LDA(At, 1, 1); PG8_STAGE(PG8_SB(1, 0), b3, voffB); PG8_STAGE(PG8_SB(1, 1), b3 + hstep, voffB); PG8_STAGE(PG8_SA(1, 0), a3, voffA);
;             PG8_WAIT_V(8); PG8_WAIT_L(0); PG8_BAR; if constexpr (!HALFU) { PG8_MMA(1, 0, At, B0); PG8_MMA(1, 1, At, B1); } PG8_BAR; PG8_SCHED;
	s_mov_b32 m0, s36
	s_nop 0
	global_load_lds_dwordx4 v128, s[28:29]
	s_mov_b32 m0, s37
	s_nop 0
	global_load_lds_dwordx4 v130, s[28:29]
	s_add_i32 s55, 0, 0x18000
	s_add_i32 s56, 0, 0x1c000
	v_add_u32_e32 v152, s55, v136
	v_add_u32_e32 v168, s56, v136
	ds_read_b128 v[140:143], v152
	ds_read_b128 v[144:147], v152 offset:1024
	ds_read_b128 v[148:151], v152 offset:2048
	ds_read_b128 v[152:155], v152 offset:3072
	ds_read_b128 v[156:159], v168
	ds_read_b128 v[160:163], v168 offset:1024
	ds_read_b128 v[164:167], v168 offset:2048
	ds_read_b128 v[168:171], v168 offset:3072
	s_add_u32 s10, s28, 0x2b0000
	s_addc_u32 s11, s29, 0
	s_mov_b32 m0, s38
	ds_read_b128 v[172:175], v139 offset:32768
	ds_read_b128 v[176:179], v139 offset:33792
	ds_read_b128 v[180:183], v139 offset:34816
	ds_read_b128 v[184:187], v139 offset:35840
	ds_read_b128 v[188:191], v139 offset:36864
	ds_read_b128 v[192:195], v139 offset:37888
	ds_read_b128 v[196:199], v139 offset:38912
	ds_read_b128 v[200:203], v139 offset:39936
	global_load_lds_dwordx4 v128, s[10:11]
	s_mov_b32 m0, s39
	s_nop 0
	global_load_lds_dwordx4 v130, s[10:11]
	s_waitcnt vmcnt(8)
	s_waitcnt lgkmcnt(0)
	s_barrier
	s_setprio 1
	s_waitcnt lgkmcnt(0)
	v_mfma_f32_16x16x32_bf16 v[124:127], v[140:143], v[172:175], v[124:127]
	v_mfma_f32_16x16x32_bf16 v[120:123], v[148:151], v[172:175], v[120:123]
	v_mfma_f32_16x16x32_bf16 v[112:115], v[140:143], v[180:183], v[112:115]
	v_mfma_f32_16x16x32_bf16 v[104:107], v[148:151], v[180:183], v[104:107]
	v_mfma_f32_16x16x32_bf16 v[96:99], v[140:143], v[188:191], v[96:99]
	v_mfma_f32_16x16x32_bf16 v[88:91], v[148:151], v[188:191], v[88:91]
	v_mfma_f32_16x16x32_bf16 v[80:83], v[140:143], v[196:199], v[80:83]
	v_mfma_f32_16x16x32_bf16 v[72:75], v[148:151], v[196:199], v[72:75]
	v_mfma_f32_16x16x32_bf16 v[124:127], v[144:147], v[176:179], v[124:127]
	v_mfma_f32_16x16x32_bf16 v[120:123], v[152:155], v[176:179], v[120:123]
	v_mfma_f32_16x16x32_bf16 v[112:115], v[144:147], v[184:187], v[112:115]
	v_mfma_f32_16x16x32_bf16 v[104:107], v[152:155], v[184:187], v[104:107]
	v_mfma_f32_16x16x32_bf16 v[96:99], v[144:147], v[192:195], v[96:99]
	v_mfma_f32_16x16x32_bf16 v[88:91], v[152:155], v[192:195], v[88:91]
	v_mfma_f32_16x16x32_bf16 v[80:83], v[144:147], v[200:203], v[80:83]
	v_mfma_f32_16x16x32_bf16 v[72:75], v[152:155], v[200:203], v[72:75]
	s_setprio 0
	s_setprio 1
	v_mfma_f32_16x16x32_bf16 v[116:119], v[156:159], v[172:175], v[116:119]
	v_mfma_f32_16x16x32_bf16 v[108:111], v[164:167], v[172:175], v[108:111]
	v_mfma_f32_16x16x32_bf16 v[100:103], v[156:159], v[180:183], v[100:103]
	v_mfma_f32_16x16x32_bf16 v[92:95], v[164:167], v[180:183], v[92:95]
	v_mfma_f32_16x16x32_bf16 v[84:87], v[156:159], v[188:191], v[84:87]
	v_mfma_f32_16x16x32_bf16 v[76:79], v[164:167], v[188:191], v[76:79]
	v_mfma_f32_16x16x32_bf16 v[68:71], v[156:159], v[196:199], v[68:71]
	v_mfma_f32_16x16x32_bf16 v[64:67], v[164:167], v[196:199], v[64:67]
	v_mfma_f32_16x16x32_bf16 v[116:119], v[160:163], v[176:179], v[116:119]
	v_mfma_f32_16x16x32_bf16 v[108:111], v[168:171], v[176:179], v[108:111]
	v_mfma_f32_16x16x32_bf16 v[100:103], v[160:163], v[184:187], v[100:103]
	v_mfma_f32_16x16x32_bf16 v[92:95], v[168:171], v[184:187], v[92:95]
	v_mfma_f32_16x16x32_bf16 v[84:87], v[160:163], v[192:195], v[84:87]
	v_mfma_f32_16x16x32_bf16 v[76:79], v[168:171], v[192:195], v[76:79]
	v_mfma_f32_16x16x32_bf16 v[68:71], v[160:163], v[200:203], v[68:71]
	v_mfma_f32_16x16x32_bf16 v[64:67], v[168:171], v[200:203], v[64:67]
	s_setprio 0
	s_barrier
	s_add_u32 s10, s26, 0x80
	s_addc_u32 s11, s27, 0
	s_add_i32 s28, s55, s31
	s_mov_b32 m0, s28
	ds_read_b128 v[172:175], v139 offset:49152
	ds_read_b128 v[176:179], v139 offset:50176
	ds_read_b128 v[180:183], v139 offset:51200
	ds_read_b128 v[184:187], v139 offset:52224
	ds_read_b128 v[188:191], v139 offset:53248
	ds_read_b128 v[192:195], v139 offset:54272
	ds_read_b128 v[196:199], v139 offset:55296
	ds_read_b128 v[200:203], v139 offset:56320
	global_load_lds_dwordx4 v128, s[10:11]
	s_add_i32 m0, s28, 0x2000
	v_lshl_add_u64 v[204:205], s[10:11], 0, v[130:131]
	s_add_u32 s10, s26, 0x2b0080
	s_addc_u32 s11, s27, 0
	s_add_i32 s26, s56, s31
	global_load_lds_dwordx4 v[204:205], off
	s_mov_b32 m0, s26
	s_nop 0
	global_load_lds_dwordx4 v128, s[10:11]
	s_add_i32 m0, s26, 0x2000
	s_nop 0
	global_load_lds_dwordx4 v130, s[10:11]
	s_waitcnt vmcnt(4)
	s_waitcnt lgkmcnt(0)
	s_barrier
	s_setprio 1
	s_waitcnt lgkmcnt(0)
	v_mfma_f32_16x16x32_bf16 v[60:63], v[140:143], v[172:175], v[60:63]
	v_mfma_f32_16x16x32_bf16 v[56:59], v[148:151], v[172:175], v[56:59]
	v_mfma_f32_16x16x32_bf16 v[48:51], v[140:143], v[180:183], v[48:51]
	v_mfma_f32_16x16x32_bf16 v[40:43], v[148:151], v[180:183], v[40:43]
	v_mfma_f32_16x16x32_bf16 v[32:35], v[140:143], v[188:191], v[32:35]
	v_mfma_f32_16x16x32_bf16 v[24:27], v[148:151], v[188:191], v[24:27]
	v_mfma_f32_16x16x32_bf16 v[16:19], v[140:143], v[196:199], v[16:19]
	v_mfma_f32_16x16x32_bf16 v[8:11], v[148:151], v[196:199], v[8:11]
	v_mfma_f32_16x16x32_bf16 v[60:63], v[144:147], v[176:179], v[60:63]
	v_mfma_f32_16x16x32_bf16 v[56:59], v[152:155], v[176:179], v[56:59]
	v_mfma_f32_16x16x32_bf16 v[48:51], v[144:147], v[184:187], v[48:51]
	v_mfma_f32_16x16x32_bf16 v[40:43], v[152:155], v[184:187], v[40:43]
	v_mfma_f32_16x16x32_bf16 v[32:35], v[144:147], v[192:195], v[32:35]
	v_mfma_f32_16x16x32_bf16 v[24:27], v[152:155], v[192:195], v[24:27]
	v_mfma_f32_16x16x32_bf16 v[16:19], v[144:147], v[200:203], v[16:19]
	v_mfma_f32_16x16x32_bf16 v[8:11], v[152:155], v[200:203], v[8:11]
	s_setprio 0
	s_setprio 1
	v_mfma_f32_16x16x32_bf16 v[52:55], v[156:159], v[172:175], v[52:55]
	v_mfma_f32_16x16x32_bf16 v[44:47], v[164:167], v[172:175], v[44:47]
	v_mfma_f32_16x16x32_bf16 v[36:39], v[156:159], v[180:183], v[36:39]
	v_mfma_f32_16x16x32_bf16 v[28:31], v[164:167], v[180:183], v[28:31]
	v_mfma_f32_16x16x32_bf16 v[20:23], v[156:159], v[188:191], v[20:23]
	v_mfma_f32_16x16x32_bf16 v[12:15], v[164:167], v[188:191], v[12:15]
	v_mfma_f32_16x16x32_bf16 v[4:7], v[156:159], v[196:199], v[4:7]
	v_mfma_f32_16x16x32_bf16 v[0:3], v[164:167], v[196:199], v[0:3]
	v_mfma_f32_16x16x32_bf16 v[52:55], v[160:163], v[176:179], v[52:55]
	v_mfma_f32_16x16x32_bf16 v[44:47], v[168:171], v[176:179], v[44:47]
	v_mfma_f32_16x16x32_bf16 v[36:39], v[160:163], v[184:187], v[36:39]
	v_mfma_f32_16x16x32_bf16 v[28:31], v[168:171], v[184:187], v[28:31]
	v_mfma_f32_16x16x32_bf16 v[20:23], v[160:163], v[192:195], v[20:23]
	v_mfma_f32_16x16x32_bf16 v[12:15], v[168:171], v[192:195], v[12:15]
	v_mfma_f32_16x16x32_bf16 v[4:7], v[160:163], v[200:203], v[4:7]
	v_mfma_f32_16x16x32_bf16 v[0:3], v[168:171], v[200:203], v[0:3]
	s_setprio 0
	s_barrier
	s_add_i32 s54, s54, 2
	s_add_u32 s52, s52, 0x100
	s_addc_u32 s53, s53, 0
	s_cmpk_gt_u32 s54, 0xa9
	s_mov_b64 s[10:11], s[22:23]
	s_cbranch_scc0 .LBB0_793
	s_and_b64 vcc, exec, s[12:13]
	s_cbranch_vccz .LBB0_796
	s_barrier

; #define PG8_WAIT_V(n) asm volatile("s_waitcnt vmcnt(" #n ")" ::: "memory")
; #define PG8_WAIT_L(n) asm volatile("s_waitcnt lgkmcnt(" #n ")" ::: "memory")
; #define PG8_BAR __builtin_amdgcn_s_barrier()
; #define PG8_SCHED __builtin_amdgcn_sched_barrier(0)
;     ...
;             PG8_LDB(B0, 0, 0); PG8_LDB(B1, 0, 1); PG8_SCHED; PG8_LDA(At, 0, 0); PG8_STAGE(PG8_SA(1, 1), a1 + hstepA, voffA);
;             PG8_WAIT_V(8); PG8_WAIT_L(0); PG8_BAR; PG8_MMA(0, 0, At, B0); PG8_MMA(0, 1, At, B1); PG8_BAR; PG8_SCHED;
;             if constexpr (!HALFU) PG8_LDA(At, 0, 1); PG8_STAGE(PG8_SB(0, 0), b2, voffB); PG8_STAGE(PG8_SB(0, 1), b2 + hstep, voffB); PG8_STAGE(PG8_SA(0, 0), a2, voffA);
;             PG8_WAIT_V(8); PG8_WAIT_L(0); PG8_BAR; if constexpr (!HALFU) { PG8_MMA(1, 0, At, B0); PG8_MMA(1, 1, At, B1); } PG8_BAR; PG8_SCHED;
.LBB0_1200:
	s_add_u32 s98, s10, 0x80
	s_addc_u32 s99, s11, 0
	s_mov_b32 m0, s68
	s_nop 0
	global_load_lds_dwordx4 v136, s[98:99]
	s_mov_b32 m0, s69
	s_nop 0
	global_load_lds_dwordx4 v140, s[98:99]
	ds_read_b128 v[128:131], v149
	ds_read_b128 v[132:135], v149 offset:1024
	ds_read_b128 v[154:157], v149 offset:2048
	ds_read_b128 v[158:161], v149 offset:3072
	ds_read_b128 v[162:165], v150
	ds_read_b128 v[166:169], v150 offset:1024
	ds_read_b128 v[170:173], v150 offset:2048
	ds_read_b128 v[174:177], v150 offset:3072
	s_add_u32 s26, s10, 0x100
	s_addc_u32 s27, s11, 0
	s_cmp_eq_u32 s76, 28
	s_cselect_b32 s50, s9, s26
	s_cselect_b32 s51, s7, s27
	s_cselect_b32 s48, s43, s74
	s_cselect_b32 s49, s41, s75
	s_add_u32 s30, s50, 0x80
	s_addc_u32 s31, s51, 0
	s_add_u32 s10, s10, 0x80080
	s_addc_u32 s11, s11, 0
	s_add_i32 m0, s57, 0xc000
	ds_read_b128 v[178:181], v151
	ds_read_b128 v[182:185], v151 offset:1024
	ds_read_b128 v[186:189], v151 offset:2048
	ds_read_b128 v[190:193], v151 offset:3072
	ds_read_b128 v[194:197], v151 offset:4096
	ds_read_b128 v[198:201], v151 offset:5120
	ds_read_b128 v[202:205], v151 offset:6144
	ds_read_b128 v[206:209], v151 offset:7168
	global_load_lds_dwordx4 v136, s[10:11]
	s_add_i32 m0, s57, 0xe000
	s_nop 0
	global_load_lds_dwordx4 v140, s[10:11]
	s_waitcnt vmcnt(8)
	s_waitcnt lgkmcnt(0)
	s_barrier
	s_setprio 1
	s_waitcnt lgkmcnt(0)
	v_mfma_scale_f32_16x16x128_f8f6f4 v[124:127], v[128:135], v[178:185], v[124:127], v152, v152 op_sel_hi:[0,0,0]
	v_mfma_scale_f32_16x16x128_f8f6f4 v[120:123], v[154:161], v[178:185], v[120:123], v152, v152 op_sel_hi:[0,0,0]
	v_mfma_scale_f32_16x16x128_f8f6f4 v[108:111], v[128:135], v[186:193], v[108:111], v152, v152 op_sel_hi:[0,0,0]
	v_mfma_scale_f32_16x16x128_f8f6f4 v[104:107], v[154:161], v[186:193], v[104:107], v152, v152 op_sel_hi:[0,0,0]
	v_mfma_scale_f32_16x16x128_f8f6f4 v[210:213], v[128:135], v[194:201], v[92:95], v152, v152 op_sel_hi:[0,0,0]
	v_mfma_scale_f32_16x16x128_f8f6f4 v[214:217], v[154:161], v[194:201], v[88:91], v152, v152 op_sel_hi:[0,0,0]
	v_mfma_scale_f32_16x16x128_f8f6f4 v[218:221], v[128:135], v[202:209], v[76:79], v152, v152 op_sel_hi:[0,0,0]
	v_mfma_scale_f32_16x16x128_f8f6f4 v[222:225], v[154:161], v[202:209], v[72:75], v152, v152 op_sel_hi:[0,0,0]
	s_setprio 0
	s_setprio 1
	v_mfma_scale_f32_16x16x128_f8f6f4 v[116:119], v[162:169], v[178:185], v[116:119], v152, v152 op_sel_hi:[0,0,0]
	v_mfma_scale_f32_16x16x128_f8f6f4 v[112:115], v[170:177], v[178:185], v[112:115], v152, v152 op_sel_hi:[0,0,0]
	v_mfma_scale_f32_16x16x128_f8f6f4 v[100:103], v[162:169], v[186:193], v[100:103], v152, v152 op_sel_hi:[0,0,0]
	v_mfma_scale_f32_16x16x128_f8f6f4 v[96:99], v[170:177], v[186:193], v[96:99], v152, v152 op_sel_hi:[0,0,0]
	v_mfma_scale_f32_16x16x128_f8f6f4 v[178:181], v[162:169], v[194:201], v[84:87], v152, v152 op_sel_hi:[0,0,0]
	v_mfma_scale_f32_16x16x128_f8f6f4 v[182:185], v[170:177], v[194:201], v[80:83], v152, v152 op_sel_hi:[0,0,0]
	v_mfma_scale_f32_16x16x128_f8f6f4 v[186:189], v[162:169], v[202:209], v[68:71], v152, v152 op_sel_hi:[0,0,0]
	v_mfma_scale_f32_16x16x128_f8f6f4 v[190:193], v[170:177], v[202:209], v[64:67], v152, v152 op_sel_hi:[0,0,0]
	s_setprio 0
	s_barrier
	s_add_i32 s10, s71, s56
	s_mov_b32 m0, s10
	s_nop 1
	global_load_lds_dwordx4 v138, s[48:49]
	s_add_i32 m0, s10, 0x2000
	s_add_u32 s10, s48, 0x80000
	s_addc_u32 s11, s49, 0
	s_add_i32 s77, s72, s56
	global_load_lds_dwordx4 v142, s[48:49]
	s_mov_b32 m0, s77
	s_nop 0
	global_load_lds_dwordx4 v138, s[10:11]
	s_add_i32 m0, s77, 0x2000
	s_nop 0
	global_load_lds_dwordx4 v142, s[10:11]
	ds_read_b128 v[64:67], v151 offset:16384
	ds_read_b128 v[68:71], v151 offset:17408
	ds_read_b128 v[72:75], v151 offset:18432
	ds_read_b128 v[76:79], v151 offset:19456
	ds_read_b128 v[80:83], v151 offset:20480
	ds_read_b128 v[84:87], v151 offset:21504
	ds_read_b128 v[88:91], v151 offset:22528
	ds_read_b128 v[92:95], v151 offset:23552
	s_waitcnt vmcnt(4)
	s_waitcnt lgkmcnt(0)
	s_barrier
	s_setprio 1
	s_waitcnt lgkmcnt(0)
	v_mfma_scale_f32_16x16x128_f8f6f4 v[60:63], v[128:135], v[64:71], v[60:63], v152, v152 op_sel_hi:[0,0,0]
	v_mfma_scale_f32_16x16x128_f8f6f4 v[56:59], v[154:161], v[64:71], v[56:59], v152, v152 op_sel_hi:[0,0,0]
	v_mfma_scale_f32_16x16x128_f8f6f4 v[194:197], v[128:135], v[72:79], v[44:47], v152, v152 op_sel_hi:[0,0,0]
	v_mfma_scale_f32_16x16x128_f8f6f4 v[198:201], v[154:161], v[72:79], v[40:43], v152, v152 op_sel_hi:[0,0,0]
	v_mfma_scale_f32_16x16x128_f8f6f4 v[202:205], v[128:135], v[80:87], v[28:31], v152, v152 op_sel_hi:[0,0,0]
	v_mfma_scale_f32_16x16x128_f8f6f4 v[206:209], v[154:161], v[80:87], v[24:27], v152, v152 op_sel_hi:[0,0,0]
	v_mfma_scale_f32_16x16x128_f8f6f4 v[226:229], v[128:135], v[88:95], v[12:15], v152, v152 op_sel_hi:[0,0,0]
	v_mfma_scale_f32_16x16x128_f8f6f4 v[230:233], v[154:161], v[88:95], v[8:11], v152, v152 op_sel_hi:[0,0,0]
	s_setprio 0
	s_setprio 1
	v_mfma_scale_f32_16x16x128_f8f6f4 v[52:55], v[162:169], v[64:71], v[52:55], v152, v152 op_sel_hi:[0,0,0]
	v_mfma_scale_f32_16x16x128_f8f6f4 v[48:51], v[170:177], v[64:71], v[48:51], v152, v152 op_sel_hi:[0,0,0]
	v_mfma_scale_f32_16x16x128_f8f6f4 v[234:237], v[162:169], v[72:79], v[36:39], v152, v152 op_sel_hi:[0,0,0]
	v_mfma_scale_f32_16x16x128_f8f6f4 v[238:241], v[170:177], v[72:79], v[32:35], v152, v152 op_sel_hi:[0,0,0]
	v_mfma_scale_f32_16x16x128_f8f6f4 v[242:245], v[162:169], v[80:87], v[20:23], v152, v152 op_sel_hi:[0,0,0]
	v_mfma_scale_f32_16x16x128_f8f6f4 v[246:249], v[170:177], v[80:87], v[16:19], v152, v152 op_sel_hi:[0,0,0]
	v_mfma_scale_f32_16x16x128_f8f6f4 v[250:253], v[162:169], v[88:95], v[4:7], v152, v152 op_sel_hi:[0,0,0]
	v_mfma_scale_f32_16x16x128_f8f6f4 v[144:147], v[170:177], v[88:95], v[0:3], v152, v152 op_sel_hi:[0,0,0]
	s_setprio 0
	s_barrier
; #define PG8_WAIT_V(n) asm volatile("s_waitcnt vmcnt(" #n ")" ::: "memory")
; #define PG8_WAIT_L(n) asm volatile("s_waitcnt lgkmcnt(" #n ")" ::: "memory")
; #define PG8_BAR __builtin_amdgcn_s_barrier()
; #define PG8_SCHED __builtin_amdgcn_sched_barrier(0)
;     ...
;             PG8_LDB(B0, 1, 0); PG8_LDB(B1, 1, 1); PG8_SCHED; PG8_LDA(At, 1, 0); PG8_STAGE(PG8_SA(0, 1), a2 + hstepA, voffA);
;             PG8_WAIT_V(8); PG8_WAIT_L(0); PG8_BAR; PG8_MMA(0, 0, At, B0); PG8_MMA(0, 1, At, B1); PG8_BAR; PG8_SCHED;
;             if constexpr (!HALFU) PG8_LDA(At, 1, 1); PG8_STAGE(PG8_SB(1, 0), b3, voffB); PG8_STAGE(PG8_SB(1, 1), b3 + hstep, voffB); PG8_STAGE(PG8_SA(1, 0), a3, voffA);
;             PG8_WAIT_V(8); PG8_WAIT_L(0); PG8_BAR; if constexpr (!HALFU) { PG8_MMA(1, 0, At, B0); PG8_MMA(1, 1, At, B1); } PG8_BAR; PG8_SCHED;
	s_mov_b32 m0, s57
	s_nop 0
	global_load_lds_dwordx4 v136, s[50:51]
	s_mov_b32 m0, s62
	s_nop 0
	global_load_lds_dwordx4 v140, s[50:51]
	s_add_i32 s77, 0, 0x18000
	v_add_u32_e32 v8, s77, v148
	s_add_i32 s78, 0, 0x1c000
	s_nop 1
	ds_read_b128 v[0:3], v8
	ds_read_b128 v[4:7], v8 offset:1024
	ds_read_b128 v[16:19], v8 offset:2048
	ds_read_b128 v[20:23], v8 offset:3072
	v_add_u32_e32 v8, s78, v148
	ds_read_b128 v[128:131], v8
	ds_read_b128 v[132:135], v8 offset:1024
	ds_read_b128 v[154:157], v8 offset:2048
	ds_read_b128 v[158:161], v8 offset:3072
	s_add_u32 s10, s50, 0x80000
	s_addc_u32 s11, s51, 0
	s_mov_b32 m0, s63
	ds_read_b128 v[8:11], v151 offset:32768
	ds_read_b128 v[12:15], v151 offset:33792
	ds_read_b128 v[24:27], v151 offset:34816
	ds_read_b128 v[28:31], v151 offset:35840
	ds_read_b128 v[32:35], v151 offset:36864
	ds_read_b128 v[36:39], v151 offset:37888
	ds_read_b128 v[40:43], v151 offset:38912
	ds_read_b128 v[44:47], v151 offset:39936
	global_load_lds_dwordx4 v136, s[10:11]
	s_mov_b32 m0, s64
	s_nop 0
	global_load_lds_dwordx4 v140, s[10:11]
	s_waitcnt vmcnt(8)
	s_waitcnt lgkmcnt(0)
	s_barrier
	s_setprio 1
	s_waitcnt lgkmcnt(0)
	v_mfma_scale_f32_16x16x128_f8f6f4 v[124:127], v[0:7], v[8:15], v[124:127], v152, v152 op_sel_hi:[0,0,0]
	v_mfma_scale_f32_16x16x128_f8f6f4 v[120:123], v[16:23], v[8:15], v[120:123], v152, v152 op_sel_hi:[0,0,0]
	v_mfma_scale_f32_16x16x128_f8f6f4 v[108:111], v[0:7], v[24:31], v[108:111], v152, v152 op_sel_hi:[0,0,0]
	v_mfma_scale_f32_16x16x128_f8f6f4 v[104:107], v[16:23], v[24:31], v[104:107], v152, v152 op_sel_hi:[0,0,0]
	v_mfma_scale_f32_16x16x128_f8f6f4 v[92:95], v[0:7], v[32:39], v[210:213], v152, v152 op_sel_hi:[0,0,0]
	v_mfma_scale_f32_16x16x128_f8f6f4 v[88:91], v[16:23], v[32:39], v[214:217], v152, v152 op_sel_hi:[0,0,0]
	v_mfma_scale_f32_16x16x128_f8f6f4 v[76:79], v[0:7], v[40:47], v[218:221], v152, v152 op_sel_hi:[0,0,0]
	v_mfma_scale_f32_16x16x128_f8f6f4 v[72:75], v[16:23], v[40:47], v[222:225], v152, v152 op_sel_hi:[0,0,0]
	s_setprio 0
	s_setprio 1
	v_mfma_scale_f32_16x16x128_f8f6f4 v[116:119], v[128:135], v[8:15], v[116:119], v152, v152 op_sel_hi:[0,0,0]
	v_mfma_scale_f32_16x16x128_f8f6f4 v[112:115], v[154:161], v[8:15], v[112:115], v152, v152 op_sel_hi:[0,0,0]
	v_mfma_scale_f32_16x16x128_f8f6f4 v[100:103], v[128:135], v[24:31], v[100:103], v152, v152 op_sel_hi:[0,0,0]
	v_mfma_scale_f32_16x16x128_f8f6f4 v[96:99], v[154:161], v[24:31], v[96:99], v152, v152 op_sel_hi:[0,0,0]
	v_mfma_scale_f32_16x16x128_f8f6f4 v[84:87], v[128:135], v[32:39], v[178:181], v152, v152 op_sel_hi:[0,0,0]
	v_mfma_scale_f32_16x16x128_f8f6f4 v[80:83], v[154:161], v[32:39], v[182:185], v152, v152 op_sel_hi:[0,0,0]
	v_mfma_scale_f32_16x16x128_f8f6f4 v[68:71], v[128:135], v[40:47], v[186:189], v152, v152 op_sel_hi:[0,0,0]
	v_mfma_scale_f32_16x16x128_f8f6f4 v[64:67], v[154:161], v[40:47], v[190:193], v152, v152 op_sel_hi:[0,0,0]
	s_setprio 0
	s_barrier
	s_add_u32 s10, s48, 0x80
	s_addc_u32 s11, s49, 0
	s_add_i32 s50, s77, s56
	s_mov_b32 m0, s50
	ds_read_b128 v[32:35], v151 offset:49152
	ds_read_b128 v[36:39], v151 offset:50176
	ds_read_b128 v[162:165], v151 offset:51200
	ds_read_b128 v[166:169], v151 offset:52224
	ds_read_b128 v[170:173], v151 offset:53248
	ds_read_b128 v[174:177], v151 offset:54272
	ds_read_b128 v[178:181], v151 offset:55296
	ds_read_b128 v[182:185], v151 offset:56320
	global_load_lds_dwordx4 v138, s[10:11]
	s_add_i32 m0, s50, 0x2000
	v_lshl_add_u64 v[8:9], s[10:11], 0, v[142:143]
	s_add_u32 s10, s48, 0x80080
	s_addc_u32 s11, s49, 0
	s_add_i32 s48, s78, s56
	global_load_lds_dwordx4 v[8:9], off
	s_mov_b32 m0, s48
	s_nop 0
	global_load_lds_dwordx4 v138, s[10:11]
	s_add_i32 m0, s48, 0x2000
	s_nop 0
	global_load_lds_dwordx4 v142, s[10:11]
	s_waitcnt vmcnt(4)
	s_waitcnt lgkmcnt(0)
	s_barrier
	s_setprio 1
	s_waitcnt lgkmcnt(0)
	v_mfma_scale_f32_16x16x128_f8f6f4 v[60:63], v[0:7], v[32:39], v[60:63], v152, v152 op_sel_hi:[0,0,0]
	v_mfma_scale_f32_16x16x128_f8f6f4 v[56:59], v[16:23], v[32:39], v[56:59], v152, v152 op_sel_hi:[0,0,0]
	v_mfma_scale_f32_16x16x128_f8f6f4 v[44:47], v[0:7], v[162:169], v[194:197], v152, v152 op_sel_hi:[0,0,0]
	v_mfma_scale_f32_16x16x128_f8f6f4 v[40:43], v[16:23], v[162:169], v[198:201], v152, v152 op_sel_hi:[0,0,0]
	v_mfma_scale_f32_16x16x128_f8f6f4 v[28:31], v[0:7], v[170:177], v[202:205], v152, v152 op_sel_hi:[0,0,0]
	v_mfma_scale_f32_16x16x128_f8f6f4 v[24:27], v[16:23], v[170:177], v[206:209], v152, v152 op_sel_hi:[0,0,0]
	v_mfma_scale_f32_16x16x128_f8f6f4 v[12:15], v[0:7], v[178:185], v[226:229], v152, v152 op_sel_hi:[0,0,0]
	v_mfma_scale_f32_16x16x128_f8f6f4 v[8:11], v[16:23], v[178:185], v[230:233], v152, v152 op_sel_hi:[0,0,0]
	s_setprio 0
	s_setprio 1
	v_mfma_scale_f32_16x16x128_f8f6f4 v[52:55], v[128:135], v[32:39], v[52:55], v152, v152 op_sel_hi:[0,0,0]
	v_mfma_scale_f32_16x16x128_f8f6f4 v[48:51], v[154:161], v[32:39], v[48:51], v152, v152 op_sel_hi:[0,0,0]
	v_mfma_scale_f32_16x16x128_f8f6f4 v[36:39], v[128:135], v[162:169], v[234:237], v152, v152 op_sel_hi:[0,0,0]
	v_mfma_scale_f32_16x16x128_f8f6f4 v[32:35], v[154:161], v[162:169], v[238:241], v152, v152 op_sel_hi:[0,0,0]
	v_mfma_scale_f32_16x16x128_f8f6f4 v[20:23], v[128:135], v[170:177], v[242:245], v152, v152 op_sel_hi:[0,0,0]
	v_mfma_scale_f32_16x16x128_f8f6f4 v[16:19], v[154:161], v[170:177], v[246:249], v152, v152 op_sel_hi:[0,0,0]
	v_mfma_scale_f32_16x16x128_f8f6f4 v[4:7], v[128:135], v[178:185], v[250:253], v152, v152 op_sel_hi:[0,0,0]
	v_mfma_scale_f32_16x16x128_f8f6f4 v[0:3], v[154:161], v[178:185], v[144:147], v152, v152 op_sel_hi:[0,0,0]
	s_setprio 0
	s_barrier
	s_add_i32 s76, s76, 2
	s_add_u32 s74, s74, 0x100
	s_addc_u32 s75, s75, 0
	s_cmp_gt_u32 s76, 29
	s_mov_b64 s[10:11], s[26:27]
	s_cbranch_scc0 .LBB0_1200
	s_and_b64 vcc, exec, s[36:37]
	s_cbranch_vccz .LBB0_1203
	s_barrier

; #define PG8_WAIT_V(n) asm volatile("s_waitcnt vmcnt(" #n ")" ::: "memory")
; #define PG8_WAIT_L(n) asm volatile("s_waitcnt lgkmcnt(" #n ")" ::: "memory")
; #define PG8_BAR __builtin_amdgcn_s_barrier()
; #define PG8_SCHED __builtin_amdgcn_sched_barrier(0)
;     ...
;             PG8_LDB(B0, 0, 0); PG8_LDB(B1, 0, 1); PG8_SCHED; PG8_LDA(At, 0, 0); PG8_STAGE(PG8_SA(1, 1), a1 + hstepA, voffA);
;             PG8_WAIT_V(8); PG8_WAIT_L(0); PG8_BAR; PG8_MMA(0, 0, At, B0); PG8_MMA(0, 1, At, B1); PG8_BAR; PG8_SCHED;
;             if constexpr (!HALFU) PG8_LDA(At, 0, 1); PG8_STAGE(PG8_SB(0, 0), b2, voffB); PG8_STAGE(PG8_SB(0, 1), b2 + hstep, voffB); PG8_STAGE(PG8_SA(0, 0), a2, voffA);
;             PG8_WAIT_V(8); PG8_WAIT_L(0); PG8_BAR; if constexpr (!HALFU) { PG8_MMA(1, 0, At, B0); PG8_MMA(1, 1, At, B1); } PG8_BAR; PG8_SCHED;
.LBB0_1370:
	s_add_u32 s98, s10, 0x80
	s_addc_u32 s99, s11, 0
	s_mov_b32 m0, s67
	s_nop 0
	global_load_lds_dwordx4 v136, s[98:99]
	s_mov_b32 m0, s68
	s_nop 0
	global_load_lds_dwordx4 v140, s[98:99]
	ds_read_b128 v[128:131], v163
	ds_read_b128 v[132:135], v163 offset:1024
	ds_read_b128 v[150:153], v163 offset:2048
	ds_read_b128 v[154:157], v163 offset:3072
	ds_read_b128 v[158:161], v164
	ds_read_b128 v[166:169], v164 offset:1024
	ds_read_b128 v[170:173], v164 offset:2048
	ds_read_b128 v[174:177], v164 offset:3072
	s_add_u32 s12, s10, 0x100
	s_addc_u32 s13, s11, 0
	s_cmp_eq_u32 s53, 60
	s_cselect_b32 s50, s7, s12
	s_cselect_b32 s51, s0, s13
	s_cselect_b32 s48, s39, s41
	s_cselect_b32 s49, s9, s52
	s_add_u32 s46, s50, 0x80
	s_addc_u32 s47, s51, 0
	s_add_u32 s10, s10, 0x100080
	s_addc_u32 s11, s11, 0
	s_add_i32 m0, s37, 0xc000
	ds_read_b128 v[178:181], v165
	ds_read_b128 v[182:185], v165 offset:1024
	ds_read_b128 v[186:189], v165 offset:2048
	ds_read_b128 v[190:193], v165 offset:3072
	ds_read_b128 v[194:197], v165 offset:4096
	ds_read_b128 v[198:201], v165 offset:5120
	ds_read_b128 v[202:205], v165 offset:6144
	ds_read_b128 v[206:209], v165 offset:7168
	global_load_lds_dwordx4 v136, s[10:11]
	s_add_i32 m0, s37, 0xe000
	s_nop 0
	global_load_lds_dwordx4 v140, s[10:11]
	s_waitcnt vmcnt(8)
	s_waitcnt lgkmcnt(0)
	s_barrier
	s_setprio 1
	s_waitcnt lgkmcnt(0)
	v_mfma_f32_16x16x32_bf16 v[124:127], v[128:131], v[178:181], v[124:127]
	v_mfma_f32_16x16x32_bf16 v[120:123], v[150:153], v[178:181], v[120:123]
	v_mfma_f32_16x16x32_bf16 v[108:111], v[128:131], v[186:189], v[108:111]
	v_mfma_f32_16x16x32_bf16 v[104:107], v[150:153], v[186:189], v[104:107]
	v_mfma_f32_16x16x32_bf16 v[92:95], v[128:131], v[194:197], v[92:95]
	v_mfma_f32_16x16x32_bf16 v[88:91], v[150:153], v[194:197], v[88:91]
	v_mfma_f32_16x16x32_bf16 v[76:79], v[128:131], v[202:205], v[76:79]
	v_mfma_f32_16x16x32_bf16 v[72:75], v[150:153], v[202:205], v[72:75]
	v_mfma_f32_16x16x32_bf16 v[124:127], v[132:135], v[182:185], v[124:127]
	v_mfma_f32_16x16x32_bf16 v[120:123], v[154:157], v[182:185], v[120:123]
	v_mfma_f32_16x16x32_bf16 v[108:111], v[132:135], v[190:193], v[108:111]
	v_mfma_f32_16x16x32_bf16 v[104:107], v[154:157], v[190:193], v[104:107]
	v_mfma_f32_16x16x32_bf16 v[92:95], v[132:135], v[198:201], v[92:95]
	v_mfma_f32_16x16x32_bf16 v[88:91], v[154:157], v[198:201], v[88:91]
	v_mfma_f32_16x16x32_bf16 v[76:79], v[132:135], v[206:209], v[76:79]
	v_mfma_f32_16x16x32_bf16 v[72:75], v[154:157], v[206:209], v[72:75]
	s_setprio 0
	s_setprio 1
	v_mfma_f32_16x16x32_bf16 v[116:119], v[158:161], v[178:181], v[116:119]
	v_mfma_f32_16x16x32_bf16 v[112:115], v[170:173], v[178:181], v[112:115]
	v_mfma_f32_16x16x32_bf16 v[100:103], v[158:161], v[186:189], v[100:103]
	v_mfma_f32_16x16x32_bf16 v[96:99], v[170:173], v[186:189], v[96:99]
	v_mfma_f32_16x16x32_bf16 v[84:87], v[158:161], v[194:197], v[84:87]
	v_mfma_f32_16x16x32_bf16 v[80:83], v[170:173], v[194:197], v[80:83]
	v_mfma_f32_16x16x32_bf16 v[68:71], v[158:161], v[202:205], v[68:71]
	v_mfma_f32_16x16x32_bf16 v[64:67], v[170:173], v[202:205], v[64:67]
	v_mfma_f32_16x16x32_bf16 v[116:119], v[166:169], v[182:185], v[116:119]
	v_mfma_f32_16x16x32_bf16 v[112:115], v[174:177], v[182:185], v[112:115]
	v_mfma_f32_16x16x32_bf16 v[100:103], v[166:169], v[190:193], v[100:103]
	v_mfma_f32_16x16x32_bf16 v[96:99], v[174:177], v[190:193], v[96:99]
	v_mfma_f32_16x16x32_bf16 v[84:87], v[166:169], v[198:201], v[84:87]
	v_mfma_f32_16x16x32_bf16 v[80:83], v[174:177], v[198:201], v[80:83]
	v_mfma_f32_16x16x32_bf16 v[68:71], v[166:169], v[206:209], v[68:71]
	v_mfma_f32_16x16x32_bf16 v[64:67], v[174:177], v[206:209], v[64:67]
	s_setprio 0
	s_barrier
	s_add_i32 s10, s71, s21
	s_mov_b32 m0, s10
	s_nop 0
	global_load_lds_dwordx4 v138, s[48:49]
	s_add_i32 m0, s10, 0x2000
	s_add_u32 s10, s48, 0x100000
	s_addc_u32 s11, s49, 0
	s_add_i32 s54, s72, s21
	global_load_lds_dwordx4 v142, s[48:49]
	s_mov_b32 m0, s54
	s_nop 0
	global_load_lds_dwordx4 v138, s[10:11]
	s_add_i32 m0, s54, 0x2000
	s_nop 0
	global_load_lds_dwordx4 v142, s[10:11]
	ds_read_b128 v[178:181], v165 offset:16384
	ds_read_b128 v[182:185], v165 offset:17408
	ds_read_b128 v[186:189], v165 offset:18432
	ds_read_b128 v[190:193], v165 offset:19456
	ds_read_b128 v[194:197], v165 offset:20480
	ds_read_b128 v[198:201], v165 offset:21504
	ds_read_b128 v[202:205], v165 offset:22528
	ds_read_b128 v[206:209], v165 offset:23552
	s_waitcnt vmcnt(4)
	s_waitcnt lgkmcnt(0)
	s_barrier
	s_setprio 1
	s_waitcnt lgkmcnt(0)
	v_mfma_f32_16x16x32_bf16 v[60:63], v[128:131], v[178:181], v[60:63]
	v_mfma_f32_16x16x32_bf16 v[56:59], v[150:153], v[178:181], v[56:59]
	v_mfma_f32_16x16x32_bf16 v[44:47], v[128:131], v[186:189], v[44:47]
	v_mfma_f32_16x16x32_bf16 v[40:43], v[150:153], v[186:189], v[40:43]
	v_mfma_f32_16x16x32_bf16 v[28:31], v[128:131], v[194:197], v[28:31]
	v_mfma_f32_16x16x32_bf16 v[24:27], v[150:153], v[194:197], v[24:27]
	v_mfma_f32_16x16x32_bf16 v[12:15], v[128:131], v[202:205], v[12:15]
	v_mfma_f32_16x16x32_bf16 v[8:11], v[150:153], v[202:205], v[8:11]
	v_mfma_f32_16x16x32_bf16 v[60:63], v[132:135], v[182:185], v[60:63]
	v_mfma_f32_16x16x32_bf16 v[56:59], v[154:157], v[182:185], v[56:59]
	v_mfma_f32_16x16x32_bf16 v[44:47], v[132:135], v[190:193], v[44:47]
	v_mfma_f32_16x16x32_bf16 v[40:43], v[154:157], v[190:193], v[40:43]
	v_mfma_f32_16x16x32_bf16 v[28:31], v[132:135], v[198:201], v[28:31]
	v_mfma_f32_16x16x32_bf16 v[24:27], v[154:157], v[198:201], v[24:27]
	v_mfma_f32_16x16x32_bf16 v[12:15], v[132:135], v[206:209], v[12:15]
	v_mfma_f32_16x16x32_bf16 v[8:11], v[154:157], v[206:209], v[8:11]
	s_setprio 0
	s_setprio 1
	v_mfma_f32_16x16x32_bf16 v[52:55], v[158:161], v[178:181], v[52:55]
	v_mfma_f32_16x16x32_bf16 v[48:51], v[170:173], v[178:181], v[48:51]
	v_mfma_f32_16x16x32_bf16 v[36:39], v[158:161], v[186:189], v[36:39]
	v_mfma_f32_16x16x32_bf16 v[32:35], v[170:173], v[186:189], v[32:35]
	v_mfma_f32_16x16x32_bf16 v[20:23], v[158:161], v[194:197], v[20:23]
	v_mfma_f32_16x16x32_bf16 v[16:19], v[170:173], v[194:197], v[16:19]
	v_mfma_f32_16x16x32_bf16 v[4:7], v[158:161], v[202:205], v[4:7]
	v_mfma_f32_16x16x32_bf16 v[0:3], v[170:173], v[202:205], v[0:3]
	v_mfma_f32_16x16x32_bf16 v[52:55], v[166:169], v[182:185], v[52:55]
	v_mfma_f32_16x16x32_bf16 v[48:51], v[174:177], v[182:185], v[48:51]
	v_mfma_f32_16x16x32_bf16 v[36:39], v[166:169], v[190:193], v[36:39]
	v_mfma_f32_16x16x32_bf16 v[32:35], v[174:177], v[190:193], v[32:35]
	v_mfma_f32_16x16x32_bf16 v[20:23], v[166:169], v[198:201], v[20:23]
	v_mfma_f32_16x16x32_bf16 v[16:19], v[174:177], v[198:201], v[16:19]
	v_mfma_f32_16x16x32_bf16 v[4:7], v[166:169], v[206:209], v[4:7]
	v_mfma_f32_16x16x32_bf16 v[0:3], v[174:177], v[206:209], v[0:3]
	s_setprio 0
	s_barrier
; #define PG8_WAIT_V(n) asm volatile("s_waitcnt vmcnt(" #n ")" ::: "memory")
; #define PG8_WAIT_L(n) asm volatile("s_waitcnt lgkmcnt(" #n ")" ::: "memory")
; #define PG8_BAR __builtin_amdgcn_s_barrier()
; #define PG8_SCHED __builtin_amdgcn_sched_barrier(0)
;     ...
;             PG8_LDB(B0, 1, 0); PG8_LDB(B1, 1, 1); PG8_SCHED; PG8_LDA(At, 1, 0); PG8_STAGE(PG8_SA(0, 1), a2 + hstepA, voffA);
;             PG8_WAIT_V(8); PG8_WAIT_L(0); PG8_BAR; PG8_MMA(0, 0, At, B0); PG8_MMA(0, 1, At, B1); PG8_BAR; PG8_SCHED;
;             if constexpr (!HALFU) PG8_LDA(At, 1, 1); PG8_STAGE(PG8_SB(1, 0), b3, voffB); PG8_STAGE(PG8_SB(1, 1), b3 + hstep, voffB); PG8_STAGE(PG8_SA(1, 0), a3, voffA);
;             PG8_WAIT_V(8); PG8_WAIT_L(0); PG8_BAR; if constexpr (!HALFU) { PG8_MMA(1, 0, At, B0); PG8_MMA(1, 1, At, B1); } PG8_BAR; PG8_SCHED;
	s_mov_b32 m0, s37
	s_nop 0
	global_load_lds_dwordx4 v136, s[50:51]
	s_mov_b32 m0, s62
	s_nop 0
	global_load_lds_dwordx4 v140, s[50:51]
	s_add_i32 s54, 0, 0x18000
	v_add_u32_e32 v144, s54, v162
	s_add_i32 s55, 0, 0x1c000
	ds_read_b128 v[128:131], v144
	ds_read_b128 v[132:135], v144 offset:1024
	ds_read_b128 v[150:153], v144 offset:2048
	ds_read_b128 v[154:157], v144 offset:3072
	v_add_u32_e32 v144, s55, v162
	ds_read_b128 v[158:161], v144
	ds_read_b128 v[166:169], v144 offset:1024
	ds_read_b128 v[170:173], v144 offset:2048
	ds_read_b128 v[174:177], v144 offset:3072
	s_add_u32 s10, s50, 0x100000
	s_addc_u32 s11, s51, 0
	s_mov_b32 m0, s63
	ds_read_b128 v[178:181], v165 offset:32768
	ds_read_b128 v[182:185], v165 offset:33792
	ds_read_b128 v[186:189], v165 offset:34816
	ds_read_b128 v[190:193], v165 offset:35840
	ds_read_b128 v[194:197], v165 offset:36864
	ds_read_b128 v[198:201], v165 offset:37888
	ds_read_b128 v[202:205], v165 offset:38912
	ds_read_b128 v[206:209], v165 offset:39936
	global_load_lds_dwordx4 v136, s[10:11]
	s_mov_b32 m0, s64
	s_nop 0
	global_load_lds_dwordx4 v140, s[10:11]
	s_waitcnt vmcnt(8)
	s_waitcnt lgkmcnt(0)
	s_barrier
	s_setprio 1
	s_waitcnt lgkmcnt(0)
	v_mfma_f32_16x16x32_bf16 v[124:127], v[128:131], v[178:181], v[124:127]
	v_mfma_f32_16x16x32_bf16 v[120:123], v[150:153], v[178:181], v[120:123]
	v_mfma_f32_16x16x32_bf16 v[108:111], v[128:131], v[186:189], v[108:111]
	v_mfma_f32_16x16x32_bf16 v[104:107], v[150:153], v[186:189], v[104:107]
	v_mfma_f32_16x16x32_bf16 v[92:95], v[128:131], v[194:197], v[92:95]
	v_mfma_f32_16x16x32_bf16 v[88:91], v[150:153], v[194:197], v[88:91]
	v_mfma_f32_16x16x32_bf16 v[76:79], v[128:131], v[202:205], v[76:79]
	v_mfma_f32_16x16x32_bf16 v[72:75], v[150:153], v[202:205], v[72:75]
	v_mfma_f32_16x16x32_bf16 v[124:127], v[132:135], v[182:185], v[124:127]
	v_mfma_f32_16x16x32_bf16 v[120:123], v[154:157], v[182:185], v[120:123]
	v_mfma_f32_16x16x32_bf16 v[108:111], v[132:135], v[190:193], v[108:111]
	v_mfma_f32_16x16x32_bf16 v[104:107], v[154:157], v[190:193], v[104:107]
	v_mfma_f32_16x16x32_bf16 v[92:95], v[132:135], v[198:201], v[92:95]
	v_mfma_f32_16x16x32_bf16 v[88:91], v[154:157], v[198:201], v[88:91]
	v_mfma_f32_16x16x32_bf16 v[76:79], v[132:135], v[206:209], v[76:79]
	v_mfma_f32_16x16x32_bf16 v[72:75], v[154:157], v[206:209], v[72:75]
	s_setprio 0
	s_setprio 1
	v_mfma_f32_16x16x32_bf16 v[116:119], v[158:161], v[178:181], v[116:119]
	v_mfma_f32_16x16x32_bf16 v[112:115], v[170:173], v[178:181], v[112:115]
	v_mfma_f32_16x16x32_bf16 v[100:103], v[158:161], v[186:189], v[100:103]
	v_mfma_f32_16x16x32_bf16 v[96:99], v[170:173], v[186:189], v[96:99]
	v_mfma_f32_16x16x32_bf16 v[84:87], v[158:161], v[194:197], v[84:87]
	v_mfma_f32_16x16x32_bf16 v[80:83], v[170:173], v[194:197], v[80:83]
	v_mfma_f32_16x16x32_bf16 v[68:71], v[158:161], v[202:205], v[68:71]
	v_mfma_f32_16x16x32_bf16 v[64:67], v[170:173], v[202:205], v[64:67]
	v_mfma_f32_16x16x32_bf16 v[116:119], v[166:169], v[182:185], v[116:119]
	v_mfma_f32_16x16x32_bf16 v[112:115], v[174:177], v[182:185], v[112:115]
	v_mfma_f32_16x16x32_bf16 v[100:103], v[166:169], v[190:193], v[100:103]
	v_mfma_f32_16x16x32_bf16 v[96:99], v[174:177], v[190:193], v[96:99]
	v_mfma_f32_16x16x32_bf16 v[84:87], v[166:169], v[198:201], v[84:87]
	v_mfma_f32_16x16x32_bf16 v[80:83], v[174:177], v[198:201], v[80:83]
	v_mfma_f32_16x16x32_bf16 v[68:71], v[166:169], v[206:209], v[68:71]
	v_mfma_f32_16x16x32_bf16 v[64:67], v[174:177], v[206:209], v[64:67]
	s_setprio 0
	s_barrier
	s_add_u32 s10, s48, 0x80
	s_addc_u32 s11, s49, 0
	s_add_i32 s50, s54, s21
	s_mov_b32 m0, s50
	ds_read_b128 v[178:181], v165 offset:49152
	ds_read_b128 v[182:185], v165 offset:50176
	ds_read_b128 v[186:189], v165 offset:51200
	ds_read_b128 v[190:193], v165 offset:52224
	ds_read_b128 v[194:197], v165 offset:53248
	ds_read_b128 v[198:201], v165 offset:54272
	ds_read_b128 v[202:205], v165 offset:55296
	ds_read_b128 v[206:209], v165 offset:56320
	global_load_lds_dwordx4 v138, s[10:11]
	s_add_i32 m0, s50, 0x2000
	v_lshl_add_u64 v[210:211], s[10:11], 0, v[142:143]
	s_add_u32 s10, s48, 0x100080
	s_addc_u32 s11, s49, 0
	s_add_i32 s48, s55, s21
	global_load_lds_dwordx4 v[210:211], off
	s_mov_b32 m0, s48
	s_nop 0
	global_load_lds_dwordx4 v138, s[10:11]
	s_add_i32 m0, s48, 0x2000
	s_nop 0
	global_load_lds_dwordx4 v142, s[10:11]
	s_waitcnt vmcnt(4)
	s_waitcnt lgkmcnt(0)
	s_barrier
	s_setprio 1
	s_waitcnt lgkmcnt(0)
	v_mfma_f32_16x16x32_bf16 v[60:63], v[128:131], v[178:181], v[60:63]
	v_mfma_f32_16x16x32_bf16 v[56:59], v[150:153], v[178:181], v[56:59]
	v_mfma_f32_16x16x32_bf16 v[44:47], v[128:131], v[186:189], v[44:47]
	v_mfma_f32_16x16x32_bf16 v[40:43], v[150:153], v[186:189], v[40:43]
	v_mfma_f32_16x16x32_bf16 v[28:31], v[128:131], v[194:197], v[28:31]
	v_mfma_f32_16x16x32_bf16 v[24:27], v[150:153], v[194:197], v[24:27]
	v_mfma_f32_16x16x32_bf16 v[12:15], v[128:131], v[202:205], v[12:15]
	v_mfma_f32_16x16x32_bf16 v[8:11], v[150:153], v[202:205], v[8:11]
	v_mfma_f32_16x16x32_bf16 v[60:63], v[132:135], v[182:185], v[60:63]
	v_mfma_f32_16x16x32_bf16 v[56:59], v[154:157], v[182:185], v[56:59]
	v_mfma_f32_16x16x32_bf16 v[44:47], v[132:135], v[190:193], v[44:47]
	v_mfma_f32_16x16x32_bf16 v[40:43], v[154:157], v[190:193], v[40:43]
	v_mfma_f32_16x16x32_bf16 v[28:31], v[132:135], v[198:201], v[28:31]
	v_mfma_f32_16x16x32_bf16 v[24:27], v[154:157], v[198:201], v[24:27]
	v_mfma_f32_16x16x32_bf16 v[12:15], v[132:135], v[206:209], v[12:15]
	v_mfma_f32_16x16x32_bf16 v[8:11], v[154:157], v[206:209], v[8:11]
	s_setprio 0
	s_setprio 1
	v_mfma_f32_16x16x32_bf16 v[52:55], v[158:161], v[178:181], v[52:55]
	v_mfma_f32_16x16x32_bf16 v[48:51], v[170:173], v[178:181], v[48:51]
	v_mfma_f32_16x16x32_bf16 v[36:39], v[158:161], v[186:189], v[36:39]
	v_mfma_f32_16x16x32_bf16 v[32:35], v[170:173], v[186:189], v[32:35]
	v_mfma_f32_16x16x32_bf16 v[20:23], v[158:161], v[194:197], v[20:23]
	v_mfma_f32_16x16x32_bf16 v[16:19], v[170:173], v[194:197], v[16:19]
	v_mfma_f32_16x16x32_bf16 v[4:7], v[158:161], v[202:205], v[4:7]
	v_mfma_f32_16x16x32_bf16 v[0:3], v[170:173], v[202:205], v[0:3]
	v_mfma_f32_16x16x32_bf16 v[52:55], v[166:169], v[182:185], v[52:55]
	v_mfma_f32_16x16x32_bf16 v[48:51], v[174:177], v[182:185], v[48:51]
	v_mfma_f32_16x16x32_bf16 v[36:39], v[166:169], v[190:193], v[36:39]
	v_mfma_f32_16x16x32_bf16 v[32:35], v[174:177], v[190:193], v[32:35]
	v_mfma_f32_16x16x32_bf16 v[20:23], v[166:169], v[198:201], v[20:23]
	v_mfma_f32_16x16x32_bf16 v[16:19], v[174:177], v[198:201], v[16:19]
	v_mfma_f32_16x16x32_bf16 v[4:7], v[166:169], v[206:209], v[4:7]
	v_mfma_f32_16x16x32_bf16 v[0:3], v[174:177], v[206:209], v[0:3]
	s_setprio 0
	s_barrier
	s_add_i32 s53, s53, 2
	s_add_u32 s41, s41, 0x100
	s_addc_u32 s52, s52, 0
	s_cmp_gt_u32 s53, 61
	s_mov_b64 s[10:11], s[12:13]
	s_cbranch_scc0 .LBB0_1370
	s_and_b64 vcc, exec, s[28:29]
	s_cbranch_vccz .LBB0_1373
	s_barrier

; #define PG8_WAIT_V(n) asm volatile("s_waitcnt vmcnt(" #n ")" ::: "memory")
; #define PG8_WAIT_L(n) asm volatile("s_waitcnt lgkmcnt(" #n ")" ::: "memory")
; #define PG8_BAR __builtin_amdgcn_s_barrier()
; #define PG8_SCHED __builtin_amdgcn_sched_barrier(0)
;     ...
;             PG8_LDB(B0, 0, 0); PG8_LDB(B1, 0, 1); PG8_SCHED; PG8_LDA(At, 0, 0); PG8_STAGE(PG8_SA(1, 1), a1 + hstepA, voffA);
;             PG8_WAIT_V(8); PG8_WAIT_L(0); PG8_BAR; PG8_MMA(0, 0, At, B0); PG8_MMA(0, 1, At, B1); PG8_BAR; PG8_SCHED;
;             if constexpr (!HALFU) PG8_LDA(At, 0, 1); PG8_STAGE(PG8_SB(0, 0), b2, voffB); PG8_STAGE(PG8_SB(0, 1), b2 + hstep, voffB); PG8_STAGE(PG8_SA(0, 0), a2, voffA);
;             PG8_WAIT_V(8); PG8_WAIT_L(0); PG8_BAR; if constexpr (!HALFU) { PG8_MMA(1, 0, At, B0); PG8_MMA(1, 1, At, B1); } PG8_BAR; PG8_SCHED;
.LBB0_3426:
	s_sub_u32 s98, s28, 0x80000
	s_subb_u32 s99, s29, 0
	s_mov_b32 m0, s50
	s_nop 0
	global_load_lds_dwordx4 v128, s[98:99]
	s_mov_b32 m0, s51
	s_nop 0
	global_load_lds_dwordx4 v130, s[98:99]
	ds_read_b128 v[142:145], v137
	ds_read_b128 v[146:149], v137 offset:1024
	ds_read_b128 v[150:153], v137 offset:2048
	ds_read_b128 v[154:157], v137 offset:3072
	ds_read_b128 v[158:161], v138
	ds_read_b128 v[162:165], v138 offset:1024
	ds_read_b128 v[166:169], v138 offset:2048
	ds_read_b128 v[170:173], v138 offset:3072
	s_cmp_eq_u32 s62, 28
	s_cselect_b32 s38, s55, s57
	s_cselect_b32 s39, s23, s59
	s_cselect_b32 s36, s56, s60
	s_cselect_b32 s37, s21, s61
	s_add_u32 s30, s38, 0x80
	s_addc_u32 s31, s39, 0
	s_add_i32 m0, s43, 0xc000
	ds_read_b128 v[174:177], v139
	ds_read_b128 v[178:181], v139 offset:1024
	ds_read_b128 v[182:185], v139 offset:2048
	ds_read_b128 v[186:189], v139 offset:3072
	ds_read_b128 v[190:193], v139 offset:4096
	ds_read_b128 v[194:197], v139 offset:5120
	ds_read_b128 v[198:201], v139 offset:6144
	ds_read_b128 v[202:205], v139 offset:7168
	global_load_lds_dwordx4 v128, s[28:29]
	s_add_i32 m0, s43, 0xe000
	s_nop 0
	global_load_lds_dwordx4 v130, s[28:29]
	s_waitcnt vmcnt(8)
	s_waitcnt lgkmcnt(0)
	s_barrier
	s_setprio 1
	s_waitcnt lgkmcnt(0)
	v_mfma_scale_f32_16x16x128_f8f6f4 v[124:127], v[142:149], v[174:181], v[124:127], v140, v140 op_sel_hi:[0,0,0]
	v_mfma_scale_f32_16x16x128_f8f6f4 v[120:123], v[150:157], v[174:181], v[120:123], v140, v140 op_sel_hi:[0,0,0]
	v_mfma_scale_f32_16x16x128_f8f6f4 v[112:115], v[142:149], v[182:189], v[112:115], v140, v140 op_sel_hi:[0,0,0]
	v_mfma_scale_f32_16x16x128_f8f6f4 v[104:107], v[150:157], v[182:189], v[104:107], v140, v140 op_sel_hi:[0,0,0]
	v_mfma_scale_f32_16x16x128_f8f6f4 v[96:99], v[142:149], v[190:197], v[96:99], v140, v140 op_sel_hi:[0,0,0]
	v_mfma_scale_f32_16x16x128_f8f6f4 v[206:209], v[150:157], v[190:197], v[88:91], v140, v140 op_sel_hi:[0,0,0]
	v_mfma_scale_f32_16x16x128_f8f6f4 v[210:213], v[142:149], v[198:205], v[80:83], v140, v140 op_sel_hi:[0,0,0]
	v_mfma_scale_f32_16x16x128_f8f6f4 v[214:217], v[150:157], v[198:205], v[72:75], v140, v140 op_sel_hi:[0,0,0]
	s_setprio 0
	s_setprio 1
	v_mfma_scale_f32_16x16x128_f8f6f4 v[116:119], v[158:165], v[174:181], v[116:119], v140, v140 op_sel_hi:[0,0,0]
	v_mfma_scale_f32_16x16x128_f8f6f4 v[108:111], v[166:173], v[174:181], v[108:111], v140, v140 op_sel_hi:[0,0,0]
	v_mfma_scale_f32_16x16x128_f8f6f4 v[100:103], v[158:165], v[182:189], v[100:103], v140, v140 op_sel_hi:[0,0,0]
	v_mfma_scale_f32_16x16x128_f8f6f4 v[174:177], v[166:173], v[182:189], v[92:95], v140, v140 op_sel_hi:[0,0,0]
	v_mfma_scale_f32_16x16x128_f8f6f4 v[178:181], v[158:165], v[190:197], v[84:87], v140, v140 op_sel_hi:[0,0,0]
	v_mfma_scale_f32_16x16x128_f8f6f4 v[182:185], v[166:173], v[190:197], v[76:79], v140, v140 op_sel_hi:[0,0,0]
	v_mfma_scale_f32_16x16x128_f8f6f4 v[186:189], v[158:165], v[198:205], v[68:71], v140, v140 op_sel_hi:[0,0,0]
	v_mfma_scale_f32_16x16x128_f8f6f4 v[190:193], v[166:173], v[198:205], v[64:67], v140, v140 op_sel_hi:[0,0,0]
	s_setprio 0
	s_barrier
	s_add_i32 s63, s53, s41
	s_mov_b32 m0, s63
	s_nop 1
	global_load_lds_dwordx4 v128, s[36:37]
	s_add_i32 m0, s63, 0x2000
	s_add_u32 s64, s36, 0x80000
	s_addc_u32 s65, s37, 0
	s_add_i32 s63, s54, s41
	global_load_lds_dwordx4 v130, s[36:37]
	s_mov_b32 m0, s63
	s_nop 0
	global_load_lds_dwordx4 v128, s[64:65]
	s_add_i32 m0, s63, 0x2000
	s_nop 0
	global_load_lds_dwordx4 v130, s[64:65]
	ds_read_b128 v[64:67], v139 offset:16384
	ds_read_b128 v[68:71], v139 offset:17408
	ds_read_b128 v[72:75], v139 offset:18432
	ds_read_b128 v[76:79], v139 offset:19456
	ds_read_b128 v[80:83], v139 offset:20480
	ds_read_b128 v[84:87], v139 offset:21504
	ds_read_b128 v[88:91], v139 offset:22528
	ds_read_b128 v[92:95], v139 offset:23552
	s_waitcnt vmcnt(4)
	s_waitcnt lgkmcnt(0)
	s_barrier
	s_setprio 1
	s_waitcnt lgkmcnt(0)
	v_mfma_scale_f32_16x16x128_f8f6f4 v[60:63], v[142:149], v[64:71], v[60:63], v140, v140 op_sel_hi:[0,0,0]
	v_mfma_scale_f32_16x16x128_f8f6f4 v[56:59], v[150:157], v[64:71], v[56:59], v140, v140 op_sel_hi:[0,0,0]
	v_mfma_scale_f32_16x16x128_f8f6f4 v[48:51], v[142:149], v[72:79], v[48:51], v140, v140 op_sel_hi:[0,0,0]
	v_mfma_scale_f32_16x16x128_f8f6f4 v[194:197], v[150:157], v[72:79], v[40:43], v140, v140 op_sel_hi:[0,0,0]
	v_mfma_scale_f32_16x16x128_f8f6f4 v[198:201], v[142:149], v[80:87], v[32:35], v140, v140 op_sel_hi:[0,0,0]
	v_mfma_scale_f32_16x16x128_f8f6f4 v[202:205], v[150:157], v[80:87], v[24:27], v140, v140 op_sel_hi:[0,0,0]
	v_mfma_scale_f32_16x16x128_f8f6f4 v[218:221], v[142:149], v[88:95], v[16:19], v140, v140 op_sel_hi:[0,0,0]
	v_mfma_scale_f32_16x16x128_f8f6f4 v[222:225], v[150:157], v[88:95], v[8:11], v140, v140 op_sel_hi:[0,0,0]
	s_setprio 0
	s_setprio 1
	v_mfma_scale_f32_16x16x128_f8f6f4 v[52:55], v[158:165], v[64:71], v[52:55], v140, v140 op_sel_hi:[0,0,0]
	v_mfma_scale_f32_16x16x128_f8f6f4 v[226:229], v[166:173], v[64:71], v[44:47], v140, v140 op_sel_hi:[0,0,0]
	v_mfma_scale_f32_16x16x128_f8f6f4 v[230:233], v[158:165], v[72:79], v[36:39], v140, v140 op_sel_hi:[0,0,0]
	v_mfma_scale_f32_16x16x128_f8f6f4 v[234:237], v[166:173], v[72:79], v[28:31], v140, v140 op_sel_hi:[0,0,0]
	v_mfma_scale_f32_16x16x128_f8f6f4 v[238:241], v[158:165], v[80:87], v[20:23], v140, v140 op_sel_hi:[0,0,0]
	v_mfma_scale_f32_16x16x128_f8f6f4 v[242:245], v[166:173], v[80:87], v[12:15], v140, v140 op_sel_hi:[0,0,0]
	v_mfma_scale_f32_16x16x128_f8f6f4 v[246:249], v[158:165], v[88:95], v[4:7], v140, v140 op_sel_hi:[0,0,0]
	v_mfma_scale_f32_16x16x128_f8f6f4 v[250:253], v[166:173], v[88:95], v[0:3], v140, v140 op_sel_hi:[0,0,0]
	s_setprio 0
	s_barrier
; #define PG8_WAIT_V(n) asm volatile("s_waitcnt vmcnt(" #n ")" ::: "memory")
; #define PG8_WAIT_L(n) asm volatile("s_waitcnt lgkmcnt(" #n ")" ::: "memory")
; #define PG8_BAR __builtin_amdgcn_s_barrier()
; #define PG8_SCHED __builtin_amdgcn_sched_barrier(0)
;     ...
;             PG8_LDB(B0, 1, 0); PG8_LDB(B1, 1, 1); PG8_SCHED; PG8_LDA(At, 1, 0); PG8_STAGE(PG8_SA(0, 1), a2 + hstepA, voffA);
;             PG8_WAIT_V(8); PG8_WAIT_L(0); PG8_BAR; PG8_MMA(0, 0, At, B0); PG8_MMA(0, 1, At, B1); PG8_BAR; PG8_SCHED;
;             if constexpr (!HALFU) PG8_LDA(At, 1, 1); PG8_STAGE(PG8_SB(1, 0), b3, voffB); PG8_STAGE(PG8_SB(1, 1), b3 + hstep, voffB); PG8_STAGE(PG8_SA(1, 0), a3, voffA);
;             PG8_WAIT_V(8); PG8_WAIT_L(0); PG8_BAR; if constexpr (!HALFU) { PG8_MMA(1, 0, At, B0); PG8_MMA(1, 1, At, B1); } PG8_BAR; PG8_SCHED;
	s_mov_b32 m0, s43
	s_nop 0
	global_load_lds_dwordx4 v128, s[38:39]
	s_mov_b32 m0, s44
	s_nop 0
	global_load_lds_dwordx4 v130, s[38:39]
	s_add_i32 s63, 0, 0x18000
	s_add_i32 s64, 0, 0x1c000
	s_nop 0
	v_add_u32_e32 v12, s63, v136
	v_add_u32_e32 v16, s64, v136
	ds_read_b128 v[0:3], v12
	ds_read_b128 v[4:7], v12 offset:1024
	ds_read_b128 v[8:11], v12 offset:2048
	ds_read_b128 v[12:15], v12 offset:3072
	ds_read_b128 v[142:145], v16
	ds_read_b128 v[146:149], v16 offset:1024
	ds_read_b128 v[150:153], v16 offset:2048
	ds_read_b128 v[154:157], v16 offset:3072
	s_add_u32 s38, s38, 0x80000
	s_addc_u32 s39, s39, 0
	s_mov_b32 m0, s45
	ds_read_b128 v[16:19], v139 offset:32768
	ds_read_b128 v[20:23], v139 offset:33792
	ds_read_b128 v[24:27], v139 offset:34816
	ds_read_b128 v[28:31], v139 offset:35840
	ds_read_b128 v[32:35], v139 offset:36864
	ds_read_b128 v[36:39], v139 offset:37888
	ds_read_b128 v[40:43], v139 offset:38912
	ds_read_b128 v[44:47], v139 offset:39936
	global_load_lds_dwordx4 v128, s[38:39]
	s_mov_b32 m0, s46
	s_nop 0
	global_load_lds_dwordx4 v130, s[38:39]
	s_waitcnt vmcnt(8)
	s_waitcnt lgkmcnt(0)
	s_barrier
	s_setprio 1
	s_waitcnt lgkmcnt(0)
	v_mfma_scale_f32_16x16x128_f8f6f4 v[124:127], v[0:7], v[16:23], v[124:127], v140, v140 op_sel_hi:[0,0,0]
	v_mfma_scale_f32_16x16x128_f8f6f4 v[120:123], v[8:15], v[16:23], v[120:123], v140, v140 op_sel_hi:[0,0,0]
	v_mfma_scale_f32_16x16x128_f8f6f4 v[112:115], v[0:7], v[24:31], v[112:115], v140, v140 op_sel_hi:[0,0,0]
	v_mfma_scale_f32_16x16x128_f8f6f4 v[104:107], v[8:15], v[24:31], v[104:107], v140, v140 op_sel_hi:[0,0,0]
	v_mfma_scale_f32_16x16x128_f8f6f4 v[96:99], v[0:7], v[32:39], v[96:99], v140, v140 op_sel_hi:[0,0,0]
	v_mfma_scale_f32_16x16x128_f8f6f4 v[88:91], v[8:15], v[32:39], v[206:209], v140, v140 op_sel_hi:[0,0,0]
	v_mfma_scale_f32_16x16x128_f8f6f4 v[80:83], v[0:7], v[40:47], v[210:213], v140, v140 op_sel_hi:[0,0,0]
	v_mfma_scale_f32_16x16x128_f8f6f4 v[72:75], v[8:15], v[40:47], v[214:217], v140, v140 op_sel_hi:[0,0,0]
	s_setprio 0
	s_setprio 1
	v_mfma_scale_f32_16x16x128_f8f6f4 v[116:119], v[142:149], v[16:23], v[116:119], v140, v140 op_sel_hi:[0,0,0]
	v_mfma_scale_f32_16x16x128_f8f6f4 v[108:111], v[150:157], v[16:23], v[108:111], v140, v140 op_sel_hi:[0,0,0]
	v_mfma_scale_f32_16x16x128_f8f6f4 v[100:103], v[142:149], v[24:31], v[100:103], v140, v140 op_sel_hi:[0,0,0]
	v_mfma_scale_f32_16x16x128_f8f6f4 v[92:95], v[150:157], v[24:31], v[174:177], v140, v140 op_sel_hi:[0,0,0]
	v_mfma_scale_f32_16x16x128_f8f6f4 v[84:87], v[142:149], v[32:39], v[178:181], v140, v140 op_sel_hi:[0,0,0]
	v_mfma_scale_f32_16x16x128_f8f6f4 v[76:79], v[150:157], v[32:39], v[182:185], v140, v140 op_sel_hi:[0,0,0]
	v_mfma_scale_f32_16x16x128_f8f6f4 v[68:71], v[142:149], v[40:47], v[186:189], v140, v140 op_sel_hi:[0,0,0]
	v_mfma_scale_f32_16x16x128_f8f6f4 v[64:67], v[150:157], v[40:47], v[190:193], v140, v140 op_sel_hi:[0,0,0]
	s_setprio 0
	s_barrier
	s_add_u32 s38, s36, 0x80
	s_addc_u32 s39, s37, 0
	s_add_i32 s63, s63, s41
	s_mov_b32 m0, s63
	ds_read_b128 v[158:161], v139 offset:49152
	ds_read_b128 v[162:165], v139 offset:50176
	ds_read_b128 v[166:169], v139 offset:51200
	ds_read_b128 v[170:173], v139 offset:52224
	ds_read_b128 v[174:177], v139 offset:53248
	ds_read_b128 v[178:181], v139 offset:54272
	ds_read_b128 v[182:185], v139 offset:55296
	ds_read_b128 v[186:189], v139 offset:56320
	global_load_lds_dwordx4 v128, s[38:39]
	s_add_i32 m0, s63, 0x2000
	s_add_u32 s36, s36, 0x80080
	v_lshl_add_u64 v[16:17], s[38:39], 0, v[130:131]
	s_addc_u32 s37, s37, 0
	s_add_i32 s38, s64, s41
	global_load_lds_dwordx4 v[16:17], off
	s_mov_b32 m0, s38
	s_nop 0
	global_load_lds_dwordx4 v128, s[36:37]
	s_add_i32 m0, s38, 0x2000
	s_nop 0
	global_load_lds_dwordx4 v130, s[36:37]
	s_waitcnt vmcnt(4)
	s_waitcnt lgkmcnt(0)
	s_barrier
	s_setprio 1
	s_waitcnt lgkmcnt(0)
	v_mfma_scale_f32_16x16x128_f8f6f4 v[60:63], v[0:7], v[158:165], v[60:63], v140, v140 op_sel_hi:[0,0,0]
	v_mfma_scale_f32_16x16x128_f8f6f4 v[56:59], v[8:15], v[158:165], v[56:59], v140, v140 op_sel_hi:[0,0,0]
	v_mfma_scale_f32_16x16x128_f8f6f4 v[48:51], v[0:7], v[166:173], v[48:51], v140, v140 op_sel_hi:[0,0,0]
	v_mfma_scale_f32_16x16x128_f8f6f4 v[40:43], v[8:15], v[166:173], v[194:197], v140, v140 op_sel_hi:[0,0,0]
	v_mfma_scale_f32_16x16x128_f8f6f4 v[32:35], v[0:7], v[174:181], v[198:201], v140, v140 op_sel_hi:[0,0,0]
	v_mfma_scale_f32_16x16x128_f8f6f4 v[24:27], v[8:15], v[174:181], v[202:205], v140, v140 op_sel_hi:[0,0,0]
	v_mfma_scale_f32_16x16x128_f8f6f4 v[16:19], v[0:7], v[182:189], v[218:221], v140, v140 op_sel_hi:[0,0,0]
	v_mfma_scale_f32_16x16x128_f8f6f4 v[8:11], v[8:15], v[182:189], v[222:225], v140, v140 op_sel_hi:[0,0,0]
	s_setprio 0
	s_setprio 1
	v_mfma_scale_f32_16x16x128_f8f6f4 v[52:55], v[142:149], v[158:165], v[52:55], v140, v140 op_sel_hi:[0,0,0]
	v_mfma_scale_f32_16x16x128_f8f6f4 v[44:47], v[150:157], v[158:165], v[226:229], v140, v140 op_sel_hi:[0,0,0]
	v_mfma_scale_f32_16x16x128_f8f6f4 v[36:39], v[142:149], v[166:173], v[230:233], v140, v140 op_sel_hi:[0,0,0]
	v_mfma_scale_f32_16x16x128_f8f6f4 v[28:31], v[150:157], v[166:173], v[234:237], v140, v140 op_sel_hi:[0,0,0]
	v_mfma_scale_f32_16x16x128_f8f6f4 v[20:23], v[142:149], v[174:181], v[238:241], v140, v140 op_sel_hi:[0,0,0]
	v_mfma_scale_f32_16x16x128_f8f6f4 v[12:15], v[150:157], v[174:181], v[242:245], v140, v140 op_sel_hi:[0,0,0]
	v_mfma_scale_f32_16x16x128_f8f6f4 v[4:7], v[142:149], v[182:189], v[246:249], v140, v140 op_sel_hi:[0,0,0]
	v_mfma_scale_f32_16x16x128_f8f6f4 v[0:3], v[150:157], v[182:189], v[250:253], v140, v140 op_sel_hi:[0,0,0]
	s_setprio 0
	s_barrier
	s_add_i32 s62, s62, 2
	s_add_u32 s57, s57, 0x100
	s_addc_u32 s59, s59, 0
	s_add_u32 s60, s60, 0x100
	s_addc_u32 s61, s61, 0
	s_add_u32 s28, s28, 0x100
	s_addc_u32 s29, s29, 0
	s_cmp_gt_u32 s62, 29
	s_cbranch_scc0 .LBB0_3426
	s_and_b64 vcc, exec, s[6:7]
	s_cbranch_vccz .LBB0_3429
	s_barrier

; #define PG8_WAIT_V(n) asm volatile("s_waitcnt vmcnt(" #n ")" ::: "memory")
; #define PG8_WAIT_L(n) asm volatile("s_waitcnt lgkmcnt(" #n ")" ::: "memory")
; #define PG8_BAR __builtin_amdgcn_s_barrier()
; #define PG8_SCHED __builtin_amdgcn_sched_barrier(0)
;     ...
;             PG8_LDB(B0, 0, 0); PG8_LDB(B1, 0, 1); PG8_SCHED; PG8_LDA(At, 0, 0); PG8_STAGE(PG8_SA(1, 1), a1 + hstepA, voffA);
;             PG8_WAIT_V(8); PG8_WAIT_L(0); PG8_BAR; PG8_MMA(0, 0, At, B0); PG8_MMA(0, 1, At, B1); PG8_BAR; PG8_SCHED;
;             if constexpr (!HALFU) PG8_LDA(At, 0, 1); PG8_STAGE(PG8_SB(0, 0), b2, voffB); PG8_STAGE(PG8_SB(0, 1), b2 + hstep, voffB); PG8_STAGE(PG8_SA(0, 0), a2, voffA);
;             PG8_WAIT_V(8); PG8_WAIT_L(0); PG8_BAR; if constexpr (!HALFU) { PG8_MMA(1, 0, At, B0); PG8_MMA(1, 1, At, B1); } PG8_BAR; PG8_SCHED;
.LBB0_3554:
	s_add_u32 s98, s24, 0x80
	s_addc_u32 s99, s25, 0
	s_mov_b32 m0, s49
	s_nop 0
	global_load_lds_dwordx4 v134, s[98:99]
	s_mov_b32 m0, s50
	s_nop 0
	global_load_lds_dwordx4 v132, s[98:99]
	ds_read_b128 v[144:147], v141
	ds_read_b128 v[148:151], v141 offset:1024
	ds_read_b128 v[152:155], v141 offset:2048
	ds_read_b128 v[156:159], v141 offset:3072
	ds_read_b128 v[160:163], v142
	ds_read_b128 v[164:167], v142 offset:1024
	ds_read_b128 v[168:171], v142 offset:2048
	ds_read_b128 v[172:175], v142 offset:3072
	s_add_u32 s26, s24, 0x100
	s_addc_u32 s27, s25, 0
	s_cmp_eq_u32 s59, 60
	s_cselect_b32 s36, s54, s26
	s_cselect_b32 s37, s15, s27
	s_cselect_b32 s30, s55, s56
	s_cselect_b32 s31, s13, s57
	s_add_u32 s28, s36, 0x80
	s_addc_u32 s29, s37, 0
	s_add_u32 s24, s24, 0x100080
	s_addc_u32 s25, s25, 0
	s_add_i32 m0, s23, 0xc000
	ds_read_b128 v[176:179], v143
	ds_read_b128 v[180:183], v143 offset:1024
	ds_read_b128 v[184:187], v143 offset:2048
	ds_read_b128 v[188:191], v143 offset:3072
	ds_read_b128 v[192:195], v143 offset:4096
	ds_read_b128 v[196:199], v143 offset:5120
	ds_read_b128 v[200:203], v143 offset:6144
	ds_read_b128 v[204:207], v143 offset:7168
	global_load_lds_dwordx4 v134, s[24:25]
	s_add_i32 m0, s23, 0xe000
	s_nop 0
	global_load_lds_dwordx4 v132, s[24:25]
	s_waitcnt vmcnt(8)
	s_waitcnt lgkmcnt(0)
	s_barrier
	s_setprio 1
	s_waitcnt lgkmcnt(0)
	v_mfma_f32_16x16x32_bf16 v[124:127], v[144:147], v[176:179], v[124:127]
	v_mfma_f32_16x16x32_bf16 v[120:123], v[152:155], v[176:179], v[120:123]
	v_mfma_f32_16x16x32_bf16 v[108:111], v[144:147], v[184:187], v[108:111]
	v_mfma_f32_16x16x32_bf16 v[104:107], v[152:155], v[184:187], v[104:107]
	v_mfma_f32_16x16x32_bf16 v[92:95], v[144:147], v[192:195], v[92:95]
	v_mfma_f32_16x16x32_bf16 v[88:91], v[152:155], v[192:195], v[88:91]
	v_mfma_f32_16x16x32_bf16 v[76:79], v[144:147], v[200:203], v[76:79]
	v_mfma_f32_16x16x32_bf16 v[72:75], v[152:155], v[200:203], v[72:75]
	v_mfma_f32_16x16x32_bf16 v[124:127], v[148:151], v[180:183], v[124:127]
	v_mfma_f32_16x16x32_bf16 v[120:123], v[156:159], v[180:183], v[120:123]
	v_mfma_f32_16x16x32_bf16 v[108:111], v[148:151], v[188:191], v[108:111]
	v_mfma_f32_16x16x32_bf16 v[104:107], v[156:159], v[188:191], v[104:107]
	v_mfma_f32_16x16x32_bf16 v[92:95], v[148:151], v[196:199], v[92:95]
	v_mfma_f32_16x16x32_bf16 v[88:91], v[156:159], v[196:199], v[88:91]
	v_mfma_f32_16x16x32_bf16 v[76:79], v[148:151], v[204:207], v[76:79]
	v_mfma_f32_16x16x32_bf16 v[72:75], v[156:159], v[204:207], v[72:75]
	s_setprio 0
	s_setprio 1
	v_mfma_f32_16x16x32_bf16 v[116:119], v[160:163], v[176:179], v[116:119]
	v_mfma_f32_16x16x32_bf16 v[112:115], v[168:171], v[176:179], v[112:115]
	v_mfma_f32_16x16x32_bf16 v[100:103], v[160:163], v[184:187], v[100:103]
	v_mfma_f32_16x16x32_bf16 v[96:99], v[168:171], v[184:187], v[96:99]
	v_mfma_f32_16x16x32_bf16 v[84:87], v[160:163], v[192:195], v[84:87]
	v_mfma_f32_16x16x32_bf16 v[80:83], v[168:171], v[192:195], v[80:83]
	v_mfma_f32_16x16x32_bf16 v[68:71], v[160:163], v[200:203], v[68:71]
	v_mfma_f32_16x16x32_bf16 v[64:67], v[168:171], v[200:203], v[64:67]
	v_mfma_f32_16x16x32_bf16 v[116:119], v[164:167], v[180:183], v[116:119]
	v_mfma_f32_16x16x32_bf16 v[112:115], v[172:175], v[180:183], v[112:115]
	v_mfma_f32_16x16x32_bf16 v[100:103], v[164:167], v[188:191], v[100:103]
	v_mfma_f32_16x16x32_bf16 v[96:99], v[172:175], v[188:191], v[96:99]
	v_mfma_f32_16x16x32_bf16 v[84:87], v[164:167], v[196:199], v[84:87]
	v_mfma_f32_16x16x32_bf16 v[80:83], v[172:175], v[196:199], v[80:83]
	v_mfma_f32_16x16x32_bf16 v[68:71], v[164:167], v[204:207], v[68:71]
	v_mfma_f32_16x16x32_bf16 v[64:67], v[172:175], v[204:207], v[64:67]
	s_setprio 0
	s_barrier
	s_add_i32 s24, s6, s40
	s_mov_b32 m0, s24
	s_nop 0
	global_load_lds_dwordx4 v128, s[30:31]
	s_add_i32 m0, s24, 0x2000
	s_add_u32 s24, s30, 0x100000
	s_addc_u32 s25, s31, 0
	s_add_i32 s60, s51, s40
	global_load_lds_dwordx4 v130, s[30:31]
	s_mov_b32 m0, s60
	s_nop 0
	global_load_lds_dwordx4 v128, s[24:25]
	s_add_i32 m0, s60, 0x2000
	s_nop 0
	global_load_lds_dwordx4 v130, s[24:25]
	ds_read_b128 v[176:179], v143 offset:16384
	ds_read_b128 v[180:183], v143 offset:17408
	ds_read_b128 v[184:187], v143 offset:18432
	ds_read_b128 v[188:191], v143 offset:19456
	ds_read_b128 v[192:195], v143 offset:20480
	ds_read_b128 v[196:199], v143 offset:21504
	ds_read_b128 v[200:203], v143 offset:22528
	ds_read_b128 v[204:207], v143 offset:23552
	s_waitcnt vmcnt(4)
	s_waitcnt lgkmcnt(0)
	s_barrier
	s_setprio 1
	s_waitcnt lgkmcnt(0)
	v_mfma_f32_16x16x32_bf16 v[60:63], v[144:147], v[176:179], v[60:63]
	v_mfma_f32_16x16x32_bf16 v[56:59], v[152:155], v[176:179], v[56:59]
	v_mfma_f32_16x16x32_bf16 v[44:47], v[144:147], v[184:187], v[44:47]
	v_mfma_f32_16x16x32_bf16 v[40:43], v[152:155], v[184:187], v[40:43]
	v_mfma_f32_16x16x32_bf16 v[28:31], v[144:147], v[192:195], v[28:31]
	v_mfma_f32_16x16x32_bf16 v[24:27], v[152:155], v[192:195], v[24:27]
	v_mfma_f32_16x16x32_bf16 v[12:15], v[144:147], v[200:203], v[12:15]
	v_mfma_f32_16x16x32_bf16 v[8:11], v[152:155], v[200:203], v[8:11]
	v_mfma_f32_16x16x32_bf16 v[60:63], v[148:151], v[180:183], v[60:63]
	v_mfma_f32_16x16x32_bf16 v[56:59], v[156:159], v[180:183], v[56:59]
	v_mfma_f32_16x16x32_bf16 v[44:47], v[148:151], v[188:191], v[44:47]
	v_mfma_f32_16x16x32_bf16 v[40:43], v[156:159], v[188:191], v[40:43]
	v_mfma_f32_16x16x32_bf16 v[28:31], v[148:151], v[196:199], v[28:31]
	v_mfma_f32_16x16x32_bf16 v[24:27], v[156:159], v[196:199], v[24:27]
	v_mfma_f32_16x16x32_bf16 v[12:15], v[148:151], v[204:207], v[12:15]
	v_mfma_f32_16x16x32_bf16 v[8:11], v[156:159], v[204:207], v[8:11]
	s_setprio 0
	s_setprio 1
	v_mfma_f32_16x16x32_bf16 v[52:55], v[160:163], v[176:179], v[52:55]
	v_mfma_f32_16x16x32_bf16 v[48:51], v[168:171], v[176:179], v[48:51]
	v_mfma_f32_16x16x32_bf16 v[36:39], v[160:163], v[184:187], v[36:39]
	v_mfma_f32_16x16x32_bf16 v[32:35], v[168:171], v[184:187], v[32:35]
	v_mfma_f32_16x16x32_bf16 v[20:23], v[160:163], v[192:195], v[20:23]
	v_mfma_f32_16x16x32_bf16 v[16:19], v[168:171], v[192:195], v[16:19]
	v_mfma_f32_16x16x32_bf16 v[4:7], v[160:163], v[200:203], v[4:7]
	v_mfma_f32_16x16x32_bf16 v[0:3], v[168:171], v[200:203], v[0:3]
	v_mfma_f32_16x16x32_bf16 v[52:55], v[164:167], v[180:183], v[52:55]
	v_mfma_f32_16x16x32_bf16 v[48:51], v[172:175], v[180:183], v[48:51]
	v_mfma_f32_16x16x32_bf16 v[36:39], v[164:167], v[188:191], v[36:39]
	v_mfma_f32_16x16x32_bf16 v[32:35], v[172:175], v[188:191], v[32:35]
	v_mfma_f32_16x16x32_bf16 v[20:23], v[164:167], v[196:199], v[20:23]
	v_mfma_f32_16x16x32_bf16 v[16:19], v[172:175], v[196:199], v[16:19]
	v_mfma_f32_16x16x32_bf16 v[4:7], v[164:167], v[204:207], v[4:7]
	v_mfma_f32_16x16x32_bf16 v[0:3], v[172:175], v[204:207], v[0:3]
	s_setprio 0
	s_barrier
; #define PG8_WAIT_V(n) asm volatile("s_waitcnt vmcnt(" #n ")" ::: "memory")
; #define PG8_WAIT_L(n) asm volatile("s_waitcnt lgkmcnt(" #n ")" ::: "memory")
; #define PG8_BAR __builtin_amdgcn_s_barrier()
; #define PG8_SCHED __builtin_amdgcn_sched_barrier(0)
;     ...
;             PG8_LDB(B0, 1, 0); PG8_LDB(B1, 1, 1); PG8_SCHED; PG8_LDA(At, 1, 0); PG8_STAGE(PG8_SA(0, 1), a2 + hstepA, voffA);
;             PG8_WAIT_V(8); PG8_WAIT_L(0); PG8_BAR; PG8_MMA(0, 0, At, B0); PG8_MMA(0, 1, At, B1); PG8_BAR; PG8_SCHED;
;             if constexpr (!HALFU) PG8_LDA(At, 1, 1); PG8_STAGE(PG8_SB(1, 0), b3, voffB); PG8_STAGE(PG8_SB(1, 1), b3 + hstep, voffB); PG8_STAGE(PG8_SA(1, 0), a3, voffA);
;             PG8_WAIT_V(8); PG8_WAIT_L(0); PG8_BAR; if constexpr (!HALFU) { PG8_MMA(1, 0, At, B0); PG8_MMA(1, 1, At, B1); } PG8_BAR; PG8_SCHED;
	s_mov_b32 m0, s23
	s_nop 0
	global_load_lds_dwordx4 v134, s[36:37]
	s_mov_b32 m0, s43
	s_nop 0
	global_load_lds_dwordx4 v132, s[36:37]
	s_add_i32 s60, 0, 0x18000
	v_add_u32_e32 v138, s60, v140
	s_add_i32 s61, 0, 0x1c000
	ds_read_b128 v[144:147], v138
	ds_read_b128 v[148:151], v138 offset:1024
	ds_read_b128 v[152:155], v138 offset:2048
	ds_read_b128 v[156:159], v138 offset:3072
	v_add_u32_e32 v138, s61, v140
	ds_read_b128 v[160:163], v138
	ds_read_b128 v[164:167], v138 offset:1024
	ds_read_b128 v[168:171], v138 offset:2048
	ds_read_b128 v[172:175], v138 offset:3072
	s_add_u32 s24, s36, 0x100000
	s_addc_u32 s25, s37, 0
	s_mov_b32 m0, s44
	ds_read_b128 v[176:179], v143 offset:32768
	ds_read_b128 v[180:183], v143 offset:33792
	ds_read_b128 v[184:187], v143 offset:34816
	ds_read_b128 v[188:191], v143 offset:35840
	ds_read_b128 v[192:195], v143 offset:36864
	ds_read_b128 v[196:199], v143 offset:37888
	ds_read_b128 v[200:203], v143 offset:38912
	ds_read_b128 v[204:207], v143 offset:39936
	global_load_lds_dwordx4 v134, s[24:25]
	s_mov_b32 m0, s45
	s_nop 0
	global_load_lds_dwordx4 v132, s[24:25]
	s_waitcnt vmcnt(8)
	s_waitcnt lgkmcnt(0)
	s_barrier
	s_setprio 1
	s_waitcnt lgkmcnt(0)
	v_mfma_f32_16x16x32_bf16 v[124:127], v[144:147], v[176:179], v[124:127]
	v_mfma_f32_16x16x32_bf16 v[120:123], v[152:155], v[176:179], v[120:123]
	v_mfma_f32_16x16x32_bf16 v[108:111], v[144:147], v[184:187], v[108:111]
	v_mfma_f32_16x16x32_bf16 v[104:107], v[152:155], v[184:187], v[104:107]
	v_mfma_f32_16x16x32_bf16 v[92:95], v[144:147], v[192:195], v[92:95]
	v_mfma_f32_16x16x32_bf16 v[88:91], v[152:155], v[192:195], v[88:91]
	v_mfma_f32_16x16x32_bf16 v[76:79], v[144:147], v[200:203], v[76:79]
	v_mfma_f32_16x16x32_bf16 v[72:75], v[152:155], v[200:203], v[72:75]
	v_mfma_f32_16x16x32_bf16 v[124:127], v[148:151], v[180:183], v[124:127]
	v_mfma_f32_16x16x32_bf16 v[120:123], v[156:159], v[180:183], v[120:123]
	v_mfma_f32_16x16x32_bf16 v[108:111], v[148:151], v[188:191], v[108:111]
	v_mfma_f32_16x16x32_bf16 v[104:107], v[156:159], v[188:191], v[104:107]
	v_mfma_f32_16x16x32_bf16 v[92:95], v[148:151], v[196:199], v[92:95]
	v_mfma_f32_16x16x32_bf16 v[88:91], v[156:159], v[196:199], v[88:91]
	v_mfma_f32_16x16x32_bf16 v[76:79], v[148:151], v[204:207], v[76:79]
	v_mfma_f32_16x16x32_bf16 v[72:75], v[156:159], v[204:207], v[72:75]
	s_setprio 0
	s_setprio 1
	v_mfma_f32_16x16x32_bf16 v[116:119], v[160:163], v[176:179], v[116:119]
	v_mfma_f32_16x16x32_bf16 v[112:115], v[168:171], v[176:179], v[112:115]
	v_mfma_f32_16x16x32_bf16 v[100:103], v[160:163], v[184:187], v[100:103]
	v_mfma_f32_16x16x32_bf16 v[96:99], v[168:171], v[184:187], v[96:99]
	v_mfma_f32_16x16x32_bf16 v[84:87], v[160:163], v[192:195], v[84:87]
	v_mfma_f32_16x16x32_bf16 v[80:83], v[168:171], v[192:195], v[80:83]
	v_mfma_f32_16x16x32_bf16 v[68:71], v[160:163], v[200:203], v[68:71]
	v_mfma_f32_16x16x32_bf16 v[64:67], v[168:171], v[200:203], v[64:67]
	v_mfma_f32_16x16x32_bf16 v[116:119], v[164:167], v[180:183], v[116:119]
	v_mfma_f32_16x16x32_bf16 v[112:115], v[172:175], v[180:183], v[112:115]
	v_mfma_f32_16x16x32_bf16 v[100:103], v[164:167], v[188:191], v[100:103]
	v_mfma_f32_16x16x32_bf16 v[96:99], v[172:175], v[188:191], v[96:99]
	v_mfma_f32_16x16x32_bf16 v[84:87], v[164:167], v[196:199], v[84:87]
	v_mfma_f32_16x16x32_bf16 v[80:83], v[172:175], v[196:199], v[80:83]
	v_mfma_f32_16x16x32_bf16 v[68:71], v[164:167], v[204:207], v[68:71]
	v_mfma_f32_16x16x32_bf16 v[64:67], v[172:175], v[204:207], v[64:67]
	s_setprio 0
	s_barrier
	s_add_u32 s24, s30, 0x80
	s_addc_u32 s25, s31, 0
	s_add_i32 s36, s60, s40
	s_mov_b32 m0, s36
	ds_read_b128 v[176:179], v143 offset:49152
	ds_read_b128 v[180:183], v143 offset:50176
	ds_read_b128 v[184:187], v143 offset:51200
	ds_read_b128 v[188:191], v143 offset:52224
	ds_read_b128 v[192:195], v143 offset:53248
	ds_read_b128 v[196:199], v143 offset:54272
	ds_read_b128 v[200:203], v143 offset:55296
	ds_read_b128 v[204:207], v143 offset:56320
	global_load_lds_dwordx4 v128, s[24:25]
	s_add_i32 m0, s36, 0x2000
	v_lshl_add_u64 v[138:139], s[24:25], 0, v[130:131]
	s_add_u32 s24, s30, 0x100080
	s_addc_u32 s25, s31, 0
	s_add_i32 s30, s61, s40
	global_load_lds_dwordx4 v[138:139], off
	s_mov_b32 m0, s30
	s_nop 0
	global_load_lds_dwordx4 v128, s[24:25]
	s_add_i32 m0, s30, 0x2000
	s_nop 0
	global_load_lds_dwordx4 v130, s[24:25]
	s_waitcnt vmcnt(4)
	s_waitcnt lgkmcnt(0)
	s_barrier
	s_setprio 1
	s_waitcnt lgkmcnt(0)
	v_mfma_f32_16x16x32_bf16 v[60:63], v[144:147], v[176:179], v[60:63]
	v_mfma_f32_16x16x32_bf16 v[56:59], v[152:155], v[176:179], v[56:59]
	v_mfma_f32_16x16x32_bf16 v[44:47], v[144:147], v[184:187], v[44:47]
	v_mfma_f32_16x16x32_bf16 v[40:43], v[152:155], v[184:187], v[40:43]
	v_mfma_f32_16x16x32_bf16 v[28:31], v[144:147], v[192:195], v[28:31]
	v_mfma_f32_16x16x32_bf16 v[24:27], v[152:155], v[192:195], v[24:27]
	v_mfma_f32_16x16x32_bf16 v[12:15], v[144:147], v[200:203], v[12:15]
	v_mfma_f32_16x16x32_bf16 v[8:11], v[152:155], v[200:203], v[8:11]
	v_mfma_f32_16x16x32_bf16 v[60:63], v[148:151], v[180:183], v[60:63]
	v_mfma_f32_16x16x32_bf16 v[56:59], v[156:159], v[180:183], v[56:59]
	v_mfma_f32_16x16x32_bf16 v[44:47], v[148:151], v[188:191], v[44:47]
	v_mfma_f32_16x16x32_bf16 v[40:43], v[156:159], v[188:191], v[40:43]
	v_mfma_f32_16x16x32_bf16 v[28:31], v[148:151], v[196:199], v[28:31]
	v_mfma_f32_16x16x32_bf16 v[24:27], v[156:159], v[196:199], v[24:27]
	v_mfma_f32_16x16x32_bf16 v[12:15], v[148:151], v[204:207], v[12:15]
	v_mfma_f32_16x16x32_bf16 v[8:11], v[156:159], v[204:207], v[8:11]
	s_setprio 0
	s_setprio 1
	v_mfma_f32_16x16x32_bf16 v[52:55], v[160:163], v[176:179], v[52:55]
	v_mfma_f32_16x16x32_bf16 v[48:51], v[168:171], v[176:179], v[48:51]
	v_mfma_f32_16x16x32_bf16 v[36:39], v[160:163], v[184:187], v[36:39]
	v_mfma_f32_16x16x32_bf16 v[32:35], v[168:171], v[184:187], v[32:35]
	v_mfma_f32_16x16x32_bf16 v[20:23], v[160:163], v[192:195], v[20:23]
	v_mfma_f32_16x16x32_bf16 v[16:19], v[168:171], v[192:195], v[16:19]
	v_mfma_f32_16x16x32_bf16 v[4:7], v[160:163], v[200:203], v[4:7]
	v_mfma_f32_16x16x32_bf16 v[0:3], v[168:171], v[200:203], v[0:3]
	v_mfma_f32_16x16x32_bf16 v[52:55], v[164:167], v[180:183], v[52:55]
	v_mfma_f32_16x16x32_bf16 v[48:51], v[172:175], v[180:183], v[48:51]
	v_mfma_f32_16x16x32_bf16 v[36:39], v[164:167], v[188:191], v[36:39]
	v_mfma_f32_16x16x32_bf16 v[32:35], v[172:175], v[188:191], v[32:35]
	v_mfma_f32_16x16x32_bf16 v[20:23], v[164:167], v[196:199], v[20:23]
	v_mfma_f32_16x16x32_bf16 v[16:19], v[172:175], v[196:199], v[16:19]
	v_mfma_f32_16x16x32_bf16 v[4:7], v[164:167], v[204:207], v[4:7]
	v_mfma_f32_16x16x32_bf16 v[0:3], v[172:175], v[204:207], v[0:3]
	s_setprio 0
	s_barrier
	s_add_i32 s59, s59, 2
	s_add_u32 s56, s56, 0x100
	s_addc_u32 s57, s57, 0
	s_cmp_gt_u32 s59, 61
	s_mov_b64 s[24:25], s[26:27]
	s_cbranch_scc0 .LBB0_3554
	s_and_b64 vcc, exec, s[10:11]
	s_cbranch_vccz .LBB0_3557
	s_barrier

; #define PG8_WAIT_V(n) asm volatile("s_waitcnt vmcnt(" #n ")" ::: "memory")
; #define PG8_WAIT_L(n) asm volatile("s_waitcnt lgkmcnt(" #n ")" ::: "memory")
; #define PG8_BAR __builtin_amdgcn_s_barrier()
; #define PG8_SCHED __builtin_amdgcn_sched_barrier(0)
;     ...
;             if constexpr (!HALFU) PG8_LDA(At, 0, 1); PG8_STAGE(PG8_SB(0, 0), b2, voffB); PG8_STAGE(PG8_SB(0, 1), b2 + hstep, voffB); PG8_STAGE(PG8_SA(0, 0), a2, voffA);
;             PG8_WAIT_V(8); PG8_WAIT_L(0); PG8_BAR; if constexpr (!HALFU) { PG8_MMA(1, 0, At, B0); PG8_MMA(1, 1, At, B1); } PG8_BAR; PG8_SCHED;
.LBB0_3640:
	s_sub_u32 s98, s10, 0x158000
	s_subb_u32 s99, s11, 0
	s_mov_b32 m0, s42
	s_nop 0
	global_load_lds_dwordx4 v128, s[98:99]
	s_mov_b32 m0, s43
	s_nop 0
	global_load_lds_dwordx4 v130, s[98:99]
	ds_read_b128 v[142:145], v137
	ds_read_b128 v[146:149], v137 offset:1024
	ds_read_b128 v[150:153], v137 offset:2048
	ds_read_b128 v[154:157], v137 offset:3072
	ds_read_b128 v[158:161], v138
	ds_read_b128 v[162:165], v138 offset:1024
	ds_read_b128 v[166:169], v138 offset:2048
	ds_read_b128 v[170:173], v138 offset:3072
	s_cmpk_eq_i32 s55, 0x52
	s_cselect_b32 s28, s6, s51
	s_cselect_b32 s29, s7, s52
	s_cselect_b32 s26, s22, s53
	s_cselect_b32 s27, s23, s54
	s_add_u32 s24, s28, 0x80
	s_addc_u32 s25, s29, 0
	s_add_i32 m0, s33, 0xc000
	ds_read_b128 v[174:177], v139
	ds_read_b128 v[178:181], v139 offset:1024
	ds_read_b128 v[182:185], v139 offset:2048
	ds_read_b128 v[186:189], v139 offset:3072
	ds_read_b128 v[190:193], v139 offset:4096
	ds_read_b128 v[194:197], v139 offset:5120
	ds_read_b128 v[198:201], v139 offset:6144
	ds_read_b128 v[202:205], v139 offset:7168
	global_load_lds_dwordx4 v128, s[10:11]
	s_add_i32 m0, s33, 0xe000
	s_nop 0
	global_load_lds_dwordx4 v130, s[10:11]
	s_waitcnt vmcnt(8)
	s_waitcnt lgkmcnt(0)
	s_barrier
	s_setprio 1
	s_waitcnt lgkmcnt(0)
	v_mfma_scale_f32_16x16x128_f8f6f4 v[124:127], v[142:149], v[174:181], v[124:127], v140, v140 op_sel_hi:[0,0,0]
	v_mfma_scale_f32_16x16x128_f8f6f4 v[120:123], v[150:157], v[174:181], v[120:123], v140, v140 op_sel_hi:[0,0,0]
	v_mfma_scale_f32_16x16x128_f8f6f4 v[112:115], v[142:149], v[182:189], v[112:115], v140, v140 op_sel_hi:[0,0,0]
	v_mfma_scale_f32_16x16x128_f8f6f4 v[104:107], v[150:157], v[182:189], v[104:107], v140, v140 op_sel_hi:[0,0,0]
	v_mfma_scale_f32_16x16x128_f8f6f4 v[96:99], v[142:149], v[190:197], v[96:99], v140, v140 op_sel_hi:[0,0,0]
	v_mfma_scale_f32_16x16x128_f8f6f4 v[206:209], v[150:157], v[190:197], v[88:91], v140, v140 op_sel_hi:[0,0,0]
	v_mfma_scale_f32_16x16x128_f8f6f4 v[210:213], v[142:149], v[198:205], v[80:83], v140, v140 op_sel_hi:[0,0,0]
	v_mfma_scale_f32_16x16x128_f8f6f4 v[214:217], v[150:157], v[198:205], v[72:75], v140, v140 op_sel_hi:[0,0,0]
	s_setprio 0
	s_setprio 1
	v_mfma_scale_f32_16x16x128_f8f6f4 v[116:119], v[158:165], v[174:181], v[116:119], v140, v140 op_sel_hi:[0,0,0]
	v_mfma_scale_f32_16x16x128_f8f6f4 v[108:111], v[166:173], v[174:181], v[108:111], v140, v140 op_sel_hi:[0,0,0]
	v_mfma_scale_f32_16x16x128_f8f6f4 v[100:103], v[158:165], v[182:189], v[100:103], v140, v140 op_sel_hi:[0,0,0]
	v_mfma_scale_f32_16x16x128_f8f6f4 v[174:177], v[166:173], v[182:189], v[92:95], v140, v140 op_sel_hi:[0,0,0]
	v_mfma_scale_f32_16x16x128_f8f6f4 v[178:181], v[158:165], v[190:197], v[84:87], v140, v140 op_sel_hi:[0,0,0]
	v_mfma_scale_f32_16x16x128_f8f6f4 v[182:185], v[166:173], v[190:197], v[76:79], v140, v140 op_sel_hi:[0,0,0]
	v_mfma_scale_f32_16x16x128_f8f6f4 v[186:189], v[158:165], v[198:205], v[68:71], v140, v140 op_sel_hi:[0,0,0]
	v_mfma_scale_f32_16x16x128_f8f6f4 v[190:193], v[166:173], v[198:205], v[64:67], v140, v140 op_sel_hi:[0,0,0]
	s_setprio 0
	s_barrier
	s_add_i32 s56, s45, s30
	s_mov_b32 m0, s56
	s_nop 1
	global_load_lds_dwordx4 v128, s[26:27]
	s_add_i32 m0, s56, 0x2000
	s_add_u32 s56, s26, 0x158000
	s_addc_u32 s57, s27, 0
	s_add_i32 s58, s46, s30
	global_load_lds_dwordx4 v130, s[26:27]
	s_mov_b32 m0, s58
	s_nop 0
	global_load_lds_dwordx4 v128, s[56:57]
	s_add_i32 m0, s58, 0x2000
	s_nop 0
	global_load_lds_dwordx4 v130, s[56:57]
	ds_read_b128 v[64:67], v139 offset:16384
	ds_read_b128 v[68:71], v139 offset:17408
	ds_read_b128 v[72:75], v139 offset:18432
	ds_read_b128 v[76:79], v139 offset:19456
	ds_read_b128 v[80:83], v139 offset:20480
	ds_read_b128 v[84:87], v139 offset:21504
	ds_read_b128 v[88:91], v139 offset:22528
	ds_read_b128 v[92:95], v139 offset:23552
	s_waitcnt vmcnt(4)
	s_waitcnt lgkmcnt(0)
	s_barrier
	s_setprio 1
	s_waitcnt lgkmcnt(0)
	v_mfma_scale_f32_16x16x128_f8f6f4 v[60:63], v[142:149], v[64:71], v[60:63], v140, v140 op_sel_hi:[0,0,0]
	v_mfma_scale_f32_16x16x128_f8f6f4 v[56:59], v[150:157], v[64:71], v[56:59], v140, v140 op_sel_hi:[0,0,0]
	v_mfma_scale_f32_16x16x128_f8f6f4 v[48:51], v[142:149], v[72:79], v[48:51], v140, v140 op_sel_hi:[0,0,0]
	v_mfma_scale_f32_16x16x128_f8f6f4 v[194:197], v[150:157], v[72:79], v[40:43], v140, v140 op_sel_hi:[0,0,0]
	v_mfma_scale_f32_16x16x128_f8f6f4 v[198:201], v[142:149], v[80:87], v[32:35], v140, v140 op_sel_hi:[0,0,0]
	v_mfma_scale_f32_16x16x128_f8f6f4 v[202:205], v[150:157], v[80:87], v[24:27], v140, v140 op_sel_hi:[0,0,0]
	v_mfma_scale_f32_16x16x128_f8f6f4 v[218:221], v[142:149], v[88:95], v[16:19], v140, v140 op_sel_hi:[0,0,0]
	v_mfma_scale_f32_16x16x128_f8f6f4 v[222:225], v[150:157], v[88:95], v[8:11], v140, v140 op_sel_hi:[0,0,0]
	s_setprio 0
	s_setprio 1
	v_mfma_scale_f32_16x16x128_f8f6f4 v[52:55], v[158:165], v[64:71], v[52:55], v140, v140 op_sel_hi:[0,0,0]
	v_mfma_scale_f32_16x16x128_f8f6f4 v[226:229], v[166:173], v[64:71], v[44:47], v140, v140 op_sel_hi:[0,0,0]
	v_mfma_scale_f32_16x16x128_f8f6f4 v[230:233], v[158:165], v[72:79], v[36:39], v140, v140 op_sel_hi:[0,0,0]
	v_mfma_scale_f32_16x16x128_f8f6f4 v[234:237], v[166:173], v[72:79], v[28:31], v140, v140 op_sel_hi:[0,0,0]
	v_mfma_scale_f32_16x16x128_f8f6f4 v[238:241], v[158:165], v[80:87], v[20:23], v140, v140 op_sel_hi:[0,0,0]
	v_mfma_scale_f32_16x16x128_f8f6f4 v[242:245], v[166:173], v[80:87], v[12:15], v140, v140 op_sel_hi:[0,0,0]
	v_mfma_scale_f32_16x16x128_f8f6f4 v[246:249], v[158:165], v[88:95], v[4:7], v140, v140 op_sel_hi:[0,0,0]
	v_mfma_scale_f32_16x16x128_f8f6f4 v[250:253], v[166:173], v[88:95], v[0:3], v140, v140 op_sel_hi:[0,0,0]
	s_setprio 0
	s_barrier
; #define PG8_WAIT_V(n) asm volatile("s_waitcnt vmcnt(" #n ")" ::: "memory")
; #define PG8_WAIT_L(n) asm volatile("s_waitcnt lgkmcnt(" #n ")" ::: "memory")
; #define PG8_BAR __builtin_amdgcn_s_barrier()
; #define PG8_SCHED __builtin_amdgcn_sched_barrier(0)
;     ...
;             PG8_LDB(B0, 1, 0); PG8_LDB(B1, 1, 1); PG8_SCHED; PG8_LDA(At, 1, 0); PG8_STAGE(PG8_SA(0, 1), a2 + hstepA, voffA);
;             PG8_WAIT_V(8); PG8_WAIT_L(0); PG8_BAR; PG8_MMA(0, 0, At, B0); PG8_MMA(0, 1, At, B1); PG8_BAR; PG8_SCHED;
;             if constexpr (!HALFU) PG8_LDA(At, 1, 1); PG8_STAGE(PG8_SB(1, 0), b3, voffB); PG8_STAGE(PG8_SB(1, 1), b3 + hstep, voffB); PG8_STAGE(PG8_SA(1, 0), a3, voffA);
;             PG8_WAIT_V(8); PG8_WAIT_L(0); PG8_BAR; if constexpr (!HALFU) { PG8_MMA(1, 0, At, B0); PG8_MMA(1, 1, At, B1); } PG8_BAR; PG8_SCHED;
;     ...
;         if constexpr (ALIGN_EPI) { if (wr == 0) PG8_BAR; }
	s_mov_b32 m0, s33
	s_nop 0
	global_load_lds_dwordx4 v128, s[28:29]
	s_mov_b32 m0, s36
	s_nop 0
	global_load_lds_dwordx4 v130, s[28:29]
	s_add_i32 s56, 0, 0x18000
	s_add_i32 s57, 0, 0x1c000
	s_nop 0
	v_add_u32_e32 v12, s56, v136
	v_add_u32_e32 v16, s57, v136
	ds_read_b128 v[0:3], v12
	ds_read_b128 v[4:7], v12 offset:1024
	ds_read_b128 v[8:11], v12 offset:2048
	ds_read_b128 v[12:15], v12 offset:3072
	ds_read_b128 v[142:145], v16
	ds_read_b128 v[146:149], v16 offset:1024
	ds_read_b128 v[150:153], v16 offset:2048
	ds_read_b128 v[154:157], v16 offset:3072
	s_add_u32 s28, s28, 0x158000
	s_addc_u32 s29, s29, 0
	s_mov_b32 m0, s37
	ds_read_b128 v[16:19], v139 offset:32768
	ds_read_b128 v[20:23], v139 offset:33792
	ds_read_b128 v[24:27], v139 offset:34816
	ds_read_b128 v[28:31], v139 offset:35840
	ds_read_b128 v[32:35], v139 offset:36864
	ds_read_b128 v[36:39], v139 offset:37888
	ds_read_b128 v[40:43], v139 offset:38912
	ds_read_b128 v[44:47], v139 offset:39936
	global_load_lds_dwordx4 v128, s[28:29]
	s_mov_b32 m0, s38
	s_nop 0
	global_load_lds_dwordx4 v130, s[28:29]
	s_waitcnt vmcnt(8)
	s_waitcnt lgkmcnt(0)
	s_barrier
	s_setprio 1
	s_waitcnt lgkmcnt(0)
	v_mfma_scale_f32_16x16x128_f8f6f4 v[124:127], v[0:7], v[16:23], v[124:127], v140, v140 op_sel_hi:[0,0,0]
	v_mfma_scale_f32_16x16x128_f8f6f4 v[120:123], v[8:15], v[16:23], v[120:123], v140, v140 op_sel_hi:[0,0,0]
	v_mfma_scale_f32_16x16x128_f8f6f4 v[112:115], v[0:7], v[24:31], v[112:115], v140, v140 op_sel_hi:[0,0,0]
	v_mfma_scale_f32_16x16x128_f8f6f4 v[104:107], v[8:15], v[24:31], v[104:107], v140, v140 op_sel_hi:[0,0,0]
	v_mfma_scale_f32_16x16x128_f8f6f4 v[96:99], v[0:7], v[32:39], v[96:99], v140, v140 op_sel_hi:[0,0,0]
	v_mfma_scale_f32_16x16x128_f8f6f4 v[88:91], v[8:15], v[32:39], v[206:209], v140, v140 op_sel_hi:[0,0,0]
	v_mfma_scale_f32_16x16x128_f8f6f4 v[80:83], v[0:7], v[40:47], v[210:213], v140, v140 op_sel_hi:[0,0,0]
	v_mfma_scale_f32_16x16x128_f8f6f4 v[72:75], v[8:15], v[40:47], v[214:217], v140, v140 op_sel_hi:[0,0,0]
	s_setprio 0
	s_setprio 1
	v_mfma_scale_f32_16x16x128_f8f6f4 v[116:119], v[142:149], v[16:23], v[116:119], v140, v140 op_sel_hi:[0,0,0]
	v_mfma_scale_f32_16x16x128_f8f6f4 v[108:111], v[150:157], v[16:23], v[108:111], v140, v140 op_sel_hi:[0,0,0]
	v_mfma_scale_f32_16x16x128_f8f6f4 v[100:103], v[142:149], v[24:31], v[100:103], v140, v140 op_sel_hi:[0,0,0]
	v_mfma_scale_f32_16x16x128_f8f6f4 v[92:95], v[150:157], v[24:31], v[174:177], v140, v140 op_sel_hi:[0,0,0]
	v_mfma_scale_f32_16x16x128_f8f6f4 v[84:87], v[142:149], v[32:39], v[178:181], v140, v140 op_sel_hi:[0,0,0]
	v_mfma_scale_f32_16x16x128_f8f6f4 v[76:79], v[150:157], v[32:39], v[182:185], v140, v140 op_sel_hi:[0,0,0]
	v_mfma_scale_f32_16x16x128_f8f6f4 v[68:71], v[142:149], v[40:47], v[186:189], v140, v140 op_sel_hi:[0,0,0]
	v_mfma_scale_f32_16x16x128_f8f6f4 v[64:67], v[150:157], v[40:47], v[190:193], v140, v140 op_sel_hi:[0,0,0]
	s_setprio 0
	s_barrier
	s_add_u32 s28, s26, 0x80
	s_addc_u32 s29, s27, 0
	s_add_i32 s56, s56, s30
	s_mov_b32 m0, s56
	ds_read_b128 v[158:161], v139 offset:49152
	ds_read_b128 v[162:165], v139 offset:50176
	ds_read_b128 v[166:169], v139 offset:51200
	ds_read_b128 v[170:173], v139 offset:52224
	ds_read_b128 v[174:177], v139 offset:53248
	ds_read_b128 v[178:181], v139 offset:54272
	ds_read_b128 v[182:185], v139 offset:55296
	ds_read_b128 v[186:189], v139 offset:56320
	global_load_lds_dwordx4 v128, s[28:29]
	s_add_i32 m0, s56, 0x2000
	s_add_u32 s26, s26, 0x158080
	v_lshl_add_u64 v[16:17], s[28:29], 0, v[130:131]
	s_addc_u32 s27, s27, 0
	s_add_i32 s28, s57, s30
	global_load_lds_dwordx4 v[16:17], off
	s_mov_b32 m0, s28
	s_nop 0
	global_load_lds_dwordx4 v128, s[26:27]
	s_add_i32 m0, s28, 0x2000
	s_nop 0
	global_load_lds_dwordx4 v130, s[26:27]
	s_waitcnt vmcnt(4)
	s_waitcnt lgkmcnt(0)
	s_barrier
	s_setprio 1
	s_waitcnt lgkmcnt(0)
	v_mfma_scale_f32_16x16x128_f8f6f4 v[60:63], v[0:7], v[158:165], v[60:63], v140, v140 op_sel_hi:[0,0,0]
	v_mfma_scale_f32_16x16x128_f8f6f4 v[56:59], v[8:15], v[158:165], v[56:59], v140, v140 op_sel_hi:[0,0,0]
	v_mfma_scale_f32_16x16x128_f8f6f4 v[48:51], v[0:7], v[166:173], v[48:51], v140, v140 op_sel_hi:[0,0,0]
	v_mfma_scale_f32_16x16x128_f8f6f4 v[40:43], v[8:15], v[166:173], v[194:197], v140, v140 op_sel_hi:[0,0,0]
	v_mfma_scale_f32_16x16x128_f8f6f4 v[32:35], v[0:7], v[174:181], v[198:201], v140, v140 op_sel_hi:[0,0,0]
	v_mfma_scale_f32_16x16x128_f8f6f4 v[24:27], v[8:15], v[174:181], v[202:205], v140, v140 op_sel_hi:[0,0,0]
	v_mfma_scale_f32_16x16x128_f8f6f4 v[16:19], v[0:7], v[182:189], v[218:221], v140, v140 op_sel_hi:[0,0,0]
	v_mfma_scale_f32_16x16x128_f8f6f4 v[8:11], v[8:15], v[182:189], v[222:225], v140, v140 op_sel_hi:[0,0,0]
	s_setprio 0
	s_setprio 1
	v_mfma_scale_f32_16x16x128_f8f6f4 v[52:55], v[142:149], v[158:165], v[52:55], v140, v140 op_sel_hi:[0,0,0]
	v_mfma_scale_f32_16x16x128_f8f6f4 v[44:47], v[150:157], v[158:165], v[226:229], v140, v140 op_sel_hi:[0,0,0]
	v_mfma_scale_f32_16x16x128_f8f6f4 v[36:39], v[142:149], v[166:173], v[230:233], v140, v140 op_sel_hi:[0,0,0]
	v_mfma_scale_f32_16x16x128_f8f6f4 v[28:31], v[150:157], v[166:173], v[234:237], v140, v140 op_sel_hi:[0,0,0]
	v_mfma_scale_f32_16x16x128_f8f6f4 v[20:23], v[142:149], v[174:181], v[238:241], v140, v140 op_sel_hi:[0,0,0]
	v_mfma_scale_f32_16x16x128_f8f6f4 v[12:15], v[150:157], v[174:181], v[242:245], v140, v140 op_sel_hi:[0,0,0]
	v_mfma_scale_f32_16x16x128_f8f6f4 v[4:7], v[142:149], v[182:189], v[246:249], v140, v140 op_sel_hi:[0,0,0]
	v_mfma_scale_f32_16x16x128_f8f6f4 v[0:3], v[150:157], v[182:189], v[250:253], v140, v140 op_sel_hi:[0,0,0]
	s_setprio 0
	s_barrier
	s_add_i32 s55, s55, 2
	s_add_u32 s51, s51, 0x100
	s_addc_u32 s52, s52, 0
	s_add_u32 s53, s53, 0x100
	s_addc_u32 s54, s54, 0
	s_add_u32 s10, s10, 0x100
	s_addc_u32 s11, s11, 0
	s_cmpk_gt_u32 s55, 0x53
	s_cbranch_scc0 .LBB0_3640
	s_and_b64 vcc, exec, s[12:13]
	s_cbranch_vccz .LBB0_3643
	s_barrier
